# weight conversion: the row loads the compiler serialised are hoisted (all rows of an item in flight, distinct registers)
# baseline (speedup 1.0000x reference)
.LBB0_11:
	s_load_dwordx2 s[36:37], s[16:17], 0x10
	s_lshr_b32 s11, s11, 22
	s_mulk_i32 s11, 0x58
	s_sub_i32 s11, s3, s11
	s_lshl_b32 s14, s11, 7
	s_and_b32 s14, s14, 0x3ff80
	s_waitcnt lgkmcnt(0)
	s_add_u32 s36, s36, s14
	s_addc_u32 s37, s37, 0
	v_lshlrev_b32_e32 v4, 2, v2
	v_lshl_add_u64 v[58:59], s[36:37], 0, v[4:5]
	v_or_b32_e32 v250, s9, v67
	v_mad_u64_u32 v[248:249], s[36:37], v250, s0, v[58:59]
	global_load_dwordx4 v[212:215], v[248:249], off
	v_or_b32_e32 v250, s9, v69
	v_mad_u64_u32 v[248:249], s[36:37], v250, s0, v[58:59]
	global_load_dwordx4 v[216:219], v[248:249], off
	v_or_b32_e32 v250, s9, v71
	v_mad_u64_u32 v[248:249], s[36:37], v250, s0, v[58:59]
	global_load_dwordx4 v[220:223], v[248:249], off
	v_or_b32_e32 v250, s9, v73
	v_mad_u64_u32 v[248:249], s[36:37], v250, s0, v[58:59]
	global_load_dwordx4 v[224:227], v[248:249], off
	v_or_b32_e32 v250, s9, v75
	v_mad_u64_u32 v[248:249], s[36:37], v250, s0, v[58:59]
	global_load_dwordx4 v[228:231], v[248:249], off
	v_or_b32_e32 v250, s9, v77
	v_mad_u64_u32 v[248:249], s[36:37], v250, s0, v[58:59]
	global_load_dwordx4 v[232:235], v[248:249], off
	v_or_b32_e32 v250, s9, v78
	v_mad_u64_u32 v[248:249], s[36:37], v250, s0, v[58:59]
	global_load_dwordx4 v[236:239], v[248:249], off
	v_mad_u64_u32 v[84:85], s[36:37], v61, s0, v[58:59]
	global_load_dwordx4 v[84:87], v[84:85], off
	v_add_u32_e32 v4, v66, v81
	s_and_b64 vcc, exec, s[4:5]
	v_add_lshl_u32 v61, v65, s9, 2
	s_waitcnt vmcnt(0)
	v_pk_mul_f32 v[86:87], v[86:87], v[62:63] op_sel_hi:[1,0]
	v_pk_mul_f32 v[62:63], v[84:85], v[62:63] op_sel_hi:[1,0]
	ds_write2_b32 v4, v62, v63 offset1:1
	ds_write2_b32 v4, v86, v87 offset0:2 offset1:3
	s_cbranch_vccnz .LBB0_13
	global_load_dword v60, v61, s[18:19] offset:32
.LBB0_13:
	v_or_b32_e32 v4, s9, v67
	v_mad_u64_u32 v[62:63], s[36:37], v4, s0, v[58:59]
	v_add_u32_e32 v83, v66, v68
	v_mov_b32_e32 v4, 1.0
	s_and_b64 vcc, exec, s[4:5]
	s_waitcnt vmcnt(0)
	v_pk_mul_f32 v[62:63], v[214:215], v[60:61] op_sel_hi:[1,0]
	v_pk_mul_f32 v[84:85], v[212:213], v[60:61] op_sel_hi:[1,0]
	v_mov_b32_e32 v60, 1.0
	ds_write2_b32 v83, v84, v85 offset1:1
	ds_write2_b32 v83, v62, v63 offset0:2 offset1:3
	s_cbranch_vccnz .LBB0_15
	global_load_dword v60, v61, s[18:19] offset:64
.LBB0_15:
	v_or_b32_e32 v62, s9, v69
	v_mad_u64_u32 v[62:63], s[36:37], v62, s0, v[58:59]
	v_add_u32_e32 v83, v66, v70
	s_and_b64 vcc, exec, s[4:5]
	s_waitcnt vmcnt(0)
	v_pk_mul_f32 v[84:85], v[216:217], v[60:61] op_sel_hi:[1,0]
	v_pk_mul_f32 v[62:63], v[218:219], v[60:61] op_sel_hi:[1,0]
	ds_write2_b32 v83, v84, v85 offset1:1
	ds_write2_b32 v83, v62, v63 offset0:2 offset1:3
	s_cbranch_vccnz .LBB0_17
	global_load_dword v4, v61, s[18:19] offset:96
.LBB0_17:
	v_or_b32_e32 v60, s9, v71
	v_mad_u64_u32 v[62:63], s[36:37], v60, s0, v[58:59]
	v_add_u32_e32 v83, v66, v72
	v_mov_b32_e32 v60, 1.0
	s_and_b64 vcc, exec, s[4:5]
	s_waitcnt vmcnt(0)
	v_pk_mul_f32 v[62:63], v[222:223], v[4:5] op_sel_hi:[1,0]
	v_pk_mul_f32 v[84:85], v[220:221], v[4:5] op_sel_hi:[1,0]
	v_mov_b32_e32 v4, 1.0
	ds_write2_b32 v83, v84, v85 offset1:1
	ds_write2_b32 v83, v62, v63 offset0:2 offset1:3
	s_cbranch_vccnz .LBB0_19
	global_load_dword v4, v61, s[18:19] offset:128
.LBB0_19:
	v_or_b32_e32 v62, s9, v73
	v_mad_u64_u32 v[62:63], s[36:37], v62, s0, v[58:59]
	v_add_u32_e32 v83, v66, v74
	s_and_b64 vcc, exec, s[4:5]
	s_waitcnt vmcnt(0)
	v_pk_mul_f32 v[84:85], v[224:225], v[4:5] op_sel_hi:[1,0]
	v_pk_mul_f32 v[62:63], v[226:227], v[4:5] op_sel_hi:[1,0]
	ds_write2_b32 v83, v84, v85 offset1:1
	ds_write2_b32 v83, v62, v63 offset0:2 offset1:3
	s_cbranch_vccnz .LBB0_21
	global_load_dword v60, v61, s[18:19] offset:160
.LBB0_21:
	v_or_b32_e32 v4, s9, v75
	v_mad_u64_u32 v[62:63], s[36:37], v4, s0, v[58:59]
	v_add_u32_e32 v62, v66, v76
	v_mov_b32_e32 v4, 1.0
	s_and_b64 vcc, exec, s[4:5]
	s_waitcnt vmcnt(0)
	v_pk_mul_f32 v[86:87], v[230:231], v[60:61] op_sel_hi:[1,0]
	v_pk_mul_f32 v[84:85], v[228:229], v[60:61] op_sel_hi:[1,0]
	v_mov_b32_e32 v60, 1.0
	ds_write2_b32 v62, v84, v85 offset1:1
	ds_write2_b32 v62, v86, v87 offset0:2 offset1:3
	s_cbranch_vccnz .LBB0_23
	global_load_dword v60, v61, s[18:19] offset:192
.LBB0_23:
	v_or_b32_e32 v63, s9, v77
	v_mad_u64_u32 v[84:85], s[36:37], v63, s0, v[58:59]
	v_add_u32_e32 v63, 0x420, v62
	s_and_b64 vcc, exec, s[4:5]
	v_add_u32_e32 v83, 0x428, v62
	s_waitcnt vmcnt(0)
	v_pk_mul_f32 v[84:85], v[232:233], v[60:61] op_sel_hi:[1,0]
	v_pk_mul_f32 v[86:87], v[234:235], v[60:61] op_sel_hi:[1,0]
	ds_write2_b32 v63, v84, v85 offset1:1
	ds_write2_b32 v83, v86, v87 offset1:1
	s_cbranch_vccnz .LBB0_25
	global_load_dword v4, v61, s[18:19] offset:224
.LBB0_25:
	v_or_b32_e32 v60, s9, v78
	v_mad_u64_u32 v[58:59], s[36:37], v60, s0, v[58:59]
	v_add_u32_e32 v63, 0x840, v62
	s_lshl_b32 s11, s11, 5
	v_add_u32_e32 v62, 0x848, v62
	s_lshl_b32 s14, s9, 1
	s_and_b32 s9, 0xffff, s11
	s_lshl_b32 s11, s9, 1
	s_and_b32 s9, s9, 0x60
	s_and_b32 s11, s11, 0x1f00
	s_or_b32 s9, s11, s9
	s_waitcnt vmcnt(0)
	v_pk_mul_f32 v[58:59], v[236:237], v[4:5] op_sel_hi:[1,0]
	v_pk_mul_f32 v[60:61], v[238:239], v[4:5] op_sel_hi:[1,0]
	ds_write2_b32 v63, v58, v59 offset1:1
	ds_write2_b32 v62, v60, v61 offset1:1
	s_waitcnt lgkmcnt(0)
	ds_read2_b32 v[58:59], v79 offset1:33
	s_waitcnt lgkmcnt(0)
	v_cvt_pk_bf16_f32 v58, v58, v59
	ds_read2_b32 v[60:61], v79 offset0:66 offset1:99
	v_or_b32_e32 v4, s9, v65
	s_waitcnt lgkmcnt(0)
	v_cvt_pk_bf16_f32 v59, v60, v61
	ds_read2_b32 v[60:61], v79 offset0:132 offset1:165
	v_lshl_add_u64 v[62:63], v[44:45], 0, s[14:15]
	v_lshlrev_b32_e32 v4, 11, v4
	s_waitcnt lgkmcnt(0)
	v_cvt_pk_bf16_f32 v60, v60, v61
	ds_read2_b32 v[84:85], v79 offset0:198 offset1:231
	s_waitcnt lgkmcnt(0)
	v_cvt_pk_bf16_f32 v61, v84, v85
	v_lshl_add_u64 v[86:87], v[62:63], 0, v[4:5]
	ds_read2_b32 v[84:85], v79 offset0:8 offset1:41
	global_store_dwordx4 v[86:87], v[58:61], off
	v_or_b32_e32 v4, s9, v67
	v_lshlrev_b32_e32 v4, 11, v4
	s_waitcnt lgkmcnt(0)
	v_cvt_pk_bf16_f32 v58, v84, v85
	ds_read2_b32 v[60:61], v79 offset0:74 offset1:107
	s_waitcnt lgkmcnt(0)
	v_cvt_pk_bf16_f32 v59, v60, v61
	ds_read2_b32 v[60:61], v79 offset0:140 offset1:173
	s_waitcnt lgkmcnt(0)
	v_cvt_pk_bf16_f32 v60, v60, v61
	ds_read2_b32 v[84:85], v79 offset0:206 offset1:239
	s_waitcnt lgkmcnt(0)
	v_cvt_pk_bf16_f32 v61, v84, v85
	v_lshl_add_u64 v[86:87], v[62:63], 0, v[4:5]
	ds_read2_b32 v[84:85], v79 offset0:16 offset1:49
	global_store_dwordx4 v[86:87], v[58:61], off
	v_or_b32_e32 v4, s9, v69
	v_lshlrev_b32_e32 v4, 11, v4
	s_waitcnt lgkmcnt(0)
	v_cvt_pk_bf16_f32 v58, v84, v85
	ds_read2_b32 v[60:61], v79 offset0:82 offset1:115
	s_waitcnt lgkmcnt(0)
	v_cvt_pk_bf16_f32 v59, v60, v61
	ds_read2_b32 v[60:61], v79 offset0:148 offset1:181
	s_waitcnt lgkmcnt(0)
	v_cvt_pk_bf16_f32 v60, v60, v61
	ds_read2_b32 v[84:85], v79 offset0:214 offset1:247
	s_waitcnt lgkmcnt(0)
	v_cvt_pk_bf16_f32 v61, v84, v85
	v_lshl_add_u64 v[86:87], v[62:63], 0, v[4:5]
	v_or_b32_e32 v4, s9, v71
	ds_read2_b32 v[84:85], v79 offset0:24 offset1:57
	global_store_dwordx4 v[86:87], v[58:61], off
	v_lshlrev_b32_e32 v4, 11, v4
	v_lshl_add_u64 v[62:63], v[62:63], 0, v[4:5]
	s_waitcnt lgkmcnt(0)
	v_cvt_pk_bf16_f32 v58, v84, v85
	ds_read2_b32 v[60:61], v79 offset0:90 offset1:123
	s_waitcnt lgkmcnt(0)
	v_cvt_pk_bf16_f32 v59, v60, v61
	ds_read2_b32 v[60:61], v79 offset0:156 offset1:189
	s_waitcnt lgkmcnt(0)
	v_cvt_pk_bf16_f32 v60, v60, v61
	ds_read2_b32 v[84:85], v79 offset0:222 offset1:255
	s_waitcnt lgkmcnt(0)
	v_cvt_pk_bf16_f32 v61, v84, v85
	global_store_dwordx4 v[62:63], v[58:61], off
	s_waitcnt lgkmcnt(0)
	s_add_i32 s11, s3, 0xfffffa80
	s_cmpk_gt_u32 s11, 0x57f
	s_cbranch_scc0 .LBB0_44

.LBB0_31:
	s_load_dwordx2 s[36:37], s[16:17], 0x30
	s_lshl_b32 s11, s3, 5
	s_and_b32 s11, s11, 0x7e0
	s_lshl_b32 s14, s11, 2
	v_lshlrev_b32_e32 v4, 2, v2
	s_waitcnt lgkmcnt(0)
	s_add_u32 s36, s36, s14
	s_addc_u32 s37, s37, 0
	v_lshl_add_u64 v[58:59], s[36:37], 0, v[4:5]
	v_or_b32_e32 v250, s9, v67
	v_mad_u64_u32 v[248:249], s[36:37], v250, s2, v[58:59]
	global_load_dwordx4 v[212:215], v[248:249], off
	v_or_b32_e32 v250, s9, v69
	v_mad_u64_u32 v[248:249], s[36:37], v250, s2, v[58:59]
	global_load_dwordx4 v[216:219], v[248:249], off
	v_or_b32_e32 v250, s9, v71
	v_mad_u64_u32 v[248:249], s[36:37], v250, s2, v[58:59]
	global_load_dwordx4 v[220:223], v[248:249], off
	v_or_b32_e32 v250, s9, v73
	v_mad_u64_u32 v[248:249], s[36:37], v250, s2, v[58:59]
	global_load_dwordx4 v[224:227], v[248:249], off
	v_or_b32_e32 v250, s9, v75
	v_mad_u64_u32 v[248:249], s[36:37], v250, s2, v[58:59]
	global_load_dwordx4 v[228:231], v[248:249], off
	v_mad_u64_u32 v[84:85], s[36:37], v61, s2, v[58:59]
	global_load_dwordx4 v[84:87], v[84:85], off
	v_add_u32_e32 v4, v66, v81
	s_and_b64 vcc, exec, s[4:5]
	v_add_lshl_u32 v61, s9, v65, 2
	s_waitcnt vmcnt(0)
	v_pk_mul_f32 v[86:87], v[86:87], v[62:63] op_sel_hi:[1,0]
	v_pk_mul_f32 v[62:63], v[84:85], v[62:63] op_sel_hi:[1,0]
	ds_write2_b32 v4, v62, v63 offset1:1
	ds_write2_b32 v4, v86, v87 offset0:2 offset1:3
	s_cbranch_vccnz .LBB0_33
	global_load_dword v60, v61, s[20:21] offset:32
.LBB0_33:
	v_or_b32_e32 v4, s9, v67
	v_mad_u64_u32 v[62:63], s[36:37], v4, s2, v[58:59]
	v_add_u32_e32 v83, v66, v68
	v_mov_b32_e32 v4, 1.0
	s_and_b64 vcc, exec, s[4:5]
	s_waitcnt vmcnt(0)
	v_pk_mul_f32 v[62:63], v[214:215], v[60:61] op_sel_hi:[1,0]
	v_pk_mul_f32 v[84:85], v[212:213], v[60:61] op_sel_hi:[1,0]
	v_mov_b32_e32 v60, 1.0
	ds_write2_b32 v83, v84, v85 offset1:1
	ds_write2_b32 v83, v62, v63 offset0:2 offset1:3
	s_cbranch_vccnz .LBB0_35
	global_load_dword v60, v61, s[20:21] offset:64
.LBB0_35:
	v_or_b32_e32 v62, s9, v69
	v_mad_u64_u32 v[62:63], s[36:37], v62, s2, v[58:59]
	v_add_u32_e32 v83, v66, v70
	s_and_b64 vcc, exec, s[4:5]
	s_waitcnt vmcnt(0)
	v_pk_mul_f32 v[84:85], v[216:217], v[60:61] op_sel_hi:[1,0]
	v_pk_mul_f32 v[62:63], v[218:219], v[60:61] op_sel_hi:[1,0]
	ds_write2_b32 v83, v84, v85 offset1:1
	ds_write2_b32 v83, v62, v63 offset0:2 offset1:3
	s_cbranch_vccnz .LBB0_37
	global_load_dword v4, v61, s[20:21] offset:96
.LBB0_37:
	v_or_b32_e32 v60, s9, v71
	v_mad_u64_u32 v[62:63], s[36:37], v60, s2, v[58:59]
	v_add_u32_e32 v83, v66, v72
	v_mov_b32_e32 v60, 1.0
	s_and_b64 vcc, exec, s[4:5]
	s_waitcnt vmcnt(0)
	v_pk_mul_f32 v[62:63], v[222:223], v[4:5] op_sel_hi:[1,0]
	v_pk_mul_f32 v[84:85], v[220:221], v[4:5] op_sel_hi:[1,0]
	v_mov_b32_e32 v4, 1.0
	ds_write2_b32 v83, v84, v85 offset1:1
	ds_write2_b32 v83, v62, v63 offset0:2 offset1:3
	s_cbranch_vccnz .LBB0_39
	global_load_dword v4, v61, s[20:21] offset:128
.LBB0_39:
	v_or_b32_e32 v62, s9, v73
	v_mad_u64_u32 v[62:63], s[36:37], v62, s2, v[58:59]
	v_add_u32_e32 v83, v66, v74
	s_and_b64 vcc, exec, s[4:5]
	s_waitcnt vmcnt(0)
	v_pk_mul_f32 v[84:85], v[224:225], v[4:5] op_sel_hi:[1,0]
	v_pk_mul_f32 v[62:63], v[226:227], v[4:5] op_sel_hi:[1,0]
	ds_write2_b32 v83, v84, v85 offset1:1
	ds_write2_b32 v83, v62, v63 offset0:2 offset1:3
	s_cbranch_vccnz .LBB0_41
	global_load_dword v60, v61, s[20:21] offset:160
.LBB0_41:
	v_or_b32_e32 v4, s9, v75
	v_mad_u64_u32 v[62:63], s[36:37], v4, s2, v[58:59]
	v_add_u32_e32 v62, v66, v76
	s_and_b64 vcc, exec, s[4:5]
	s_waitcnt vmcnt(0)
	v_pk_mul_f32 v[84:85], v[228:229], v[60:61] op_sel_hi:[1,0]
	v_pk_mul_f32 v[86:87], v[230:231], v[60:61] op_sel_hi:[1,0]
	ds_write2_b32 v62, v84, v85 offset1:1
	ds_write2_b32 v62, v86, v87 offset0:2 offset1:3
	s_cbranch_vccnz .LBB0_82
	global_load_dword v4, v61, s[20:21] offset:192
	s_branch .LBB0_83

.LBB0_46:
	s_load_dwordx2 s[36:37], s[16:17], 0x18
	s_lshr_b32 s14, s14, 22
	s_mulk_i32 s14, 0x58
	s_sub_i32 s11, s11, s14
	s_lshl_b32 s14, s11, 7
	s_and_b32 s14, s14, 0x3ff80
	s_waitcnt lgkmcnt(0)
	s_add_u32 s36, s36, s14
	s_addc_u32 s37, s37, 0
	v_lshlrev_b32_e32 v4, 2, v2
	v_lshl_add_u64 v[58:59], s[36:37], 0, v[4:5]
	v_or_b32_e32 v250, s9, v67
	v_mad_u64_u32 v[248:249], s[36:37], v250, s0, v[58:59]
	global_load_dwordx4 v[212:215], v[248:249], off
	v_or_b32_e32 v250, s9, v69
	v_mad_u64_u32 v[248:249], s[36:37], v250, s0, v[58:59]
	global_load_dwordx4 v[216:219], v[248:249], off
	v_or_b32_e32 v250, s9, v71
	v_mad_u64_u32 v[248:249], s[36:37], v250, s0, v[58:59]
	global_load_dwordx4 v[220:223], v[248:249], off
	v_or_b32_e32 v250, s9, v73
	v_mad_u64_u32 v[248:249], s[36:37], v250, s0, v[58:59]
	global_load_dwordx4 v[224:227], v[248:249], off
	v_or_b32_e32 v250, s9, v75
	v_mad_u64_u32 v[248:249], s[36:37], v250, s0, v[58:59]
	global_load_dwordx4 v[228:231], v[248:249], off
	v_or_b32_e32 v250, s9, v77
	v_mad_u64_u32 v[248:249], s[36:37], v250, s0, v[58:59]
	global_load_dwordx4 v[232:235], v[248:249], off
	v_or_b32_e32 v250, s9, v78
	v_mad_u64_u32 v[248:249], s[36:37], v250, s0, v[58:59]
	global_load_dwordx4 v[236:239], v[248:249], off
	v_mad_u64_u32 v[84:85], s[36:37], v61, s0, v[58:59]
	global_load_dwordx4 v[84:87], v[84:85], off
	v_add_u32_e32 v4, v66, v81
	s_and_b64 vcc, exec, s[4:5]
	v_add_lshl_u32 v61, v65, s9, 2
	s_waitcnt vmcnt(0)
	v_pk_mul_f32 v[86:87], v[86:87], v[62:63] op_sel_hi:[1,0]
	v_pk_mul_f32 v[62:63], v[84:85], v[62:63] op_sel_hi:[1,0]
	ds_write2_b32 v4, v62, v63 offset1:1
	ds_write2_b32 v4, v86, v87 offset0:2 offset1:3
	s_cbranch_vccnz .LBB0_48
	global_load_dword v60, v61, s[18:19] offset:32

.LBB0_60:
	v_or_b32_e32 v60, s9, v78
	v_mad_u64_u32 v[58:59], s[4:5], v60, s0, v[58:59]
	s_lshl_b32 s4, s11, 5
	s_and_b32 s4, 0xffff, s4
	v_add_u32_e32 v63, 0x840, v62
	s_lshl_b32 s5, s4, 1
	v_add_u32_e32 v62, 0x848, v62
	s_and_b32 s4, s4, 0x60
	s_and_b32 s5, s5, 0x1f00
	s_or_b32 s4, s5, s4
	s_lshl_b32 s14, s9, 1
	s_waitcnt vmcnt(0)
	v_pk_mul_f32 v[58:59], v[236:237], v[4:5] op_sel_hi:[1,0]
	v_pk_mul_f32 v[60:61], v[238:239], v[4:5] op_sel_hi:[1,0]
	ds_write2_b32 v63, v58, v59 offset1:1
	ds_write2_b32 v62, v60, v61 offset1:1
	s_waitcnt lgkmcnt(0)
	v_or_b32_e32 v4, s4, v65
	ds_read2_b32 v[58:59], v79 offset1:33
	v_lshl_add_u64 v[62:63], v[44:45], 0, s[14:15]
	v_lshlrev_b32_e32 v4, 11, v4
	s_waitcnt lgkmcnt(0)
	v_cvt_pk_bf16_f32 v58, v58, v59
	ds_read2_b32 v[60:61], v79 offset0:66 offset1:99
	v_lshl_add_u64 v[86:87], v[62:63], 0, v[4:5]
	s_waitcnt lgkmcnt(0)
	v_cvt_pk_bf16_f32 v59, v60, v61
	ds_read2_b32 v[60:61], v79 offset0:132 offset1:165
	v_add_co_u32_e32 v86, vcc, s1, v86
	v_or_b32_e32 v4, s4, v67
	s_waitcnt lgkmcnt(0)
	v_cvt_pk_bf16_f32 v60, v60, v61
	ds_read2_b32 v[84:85], v79 offset0:198 offset1:231
	s_waitcnt lgkmcnt(0)
	v_cvt_pk_bf16_f32 v61, v84, v85
	v_addc_co_u32_e32 v87, vcc, 0, v87, vcc
	v_lshlrev_b32_e32 v4, 11, v4
	ds_read2_b32 v[84:85], v79 offset0:8 offset1:41
	global_store_dwordx4 v[86:87], v[58:61], off
	v_lshl_add_u64 v[86:87], v[62:63], 0, v[4:5]
	v_add_co_u32_e32 v86, vcc, s1, v86
	s_waitcnt lgkmcnt(0)
	v_cvt_pk_bf16_f32 v58, v84, v85
	ds_read2_b32 v[60:61], v79 offset0:74 offset1:107
	s_waitcnt lgkmcnt(0)
	v_cvt_pk_bf16_f32 v59, v60, v61
	ds_read2_b32 v[60:61], v79 offset0:140 offset1:173
	v_or_b32_e32 v4, s4, v69
	s_waitcnt lgkmcnt(0)
	v_cvt_pk_bf16_f32 v60, v60, v61
	ds_read2_b32 v[84:85], v79 offset0:206 offset1:239
	s_waitcnt lgkmcnt(0)
	v_cvt_pk_bf16_f32 v61, v84, v85
	v_addc_co_u32_e32 v87, vcc, 0, v87, vcc
	v_lshlrev_b32_e32 v4, 11, v4
	ds_read2_b32 v[84:85], v79 offset0:16 offset1:49
	global_store_dwordx4 v[86:87], v[58:61], off
	v_lshl_add_u64 v[86:87], v[62:63], 0, v[4:5]
	v_or_b32_e32 v4, s4, v71
	s_waitcnt lgkmcnt(0)
	v_cvt_pk_bf16_f32 v58, v84, v85
	ds_read2_b32 v[60:61], v79 offset0:82 offset1:115
	s_waitcnt lgkmcnt(0)
	v_cvt_pk_bf16_f32 v59, v60, v61
	ds_read2_b32 v[60:61], v79 offset0:148 offset1:181
	v_add_co_u32_e32 v86, vcc, s1, v86
	v_lshlrev_b32_e32 v4, 11, v4
	s_waitcnt lgkmcnt(0)
	v_cvt_pk_bf16_f32 v60, v60, v61
	ds_read2_b32 v[84:85], v79 offset0:214 offset1:247
	s_waitcnt lgkmcnt(0)
	v_cvt_pk_bf16_f32 v61, v84, v85
	v_addc_co_u32_e32 v87, vcc, 0, v87, vcc
	v_lshl_add_u64 v[62:63], v[62:63], 0, v[4:5]
	ds_read2_b32 v[84:85], v79 offset0:24 offset1:57
	global_store_dwordx4 v[86:87], v[58:61], off
	v_add_co_u32_e32 v62, vcc, 0x40000, v62
	s_waitcnt lgkmcnt(0)
	v_cvt_pk_bf16_f32 v58, v84, v85
	ds_read2_b32 v[60:61], v79 offset0:90 offset1:123
	s_waitcnt lgkmcnt(0)
	v_cvt_pk_bf16_f32 v59, v60, v61
	ds_read2_b32 v[60:61], v79 offset0:156 offset1:189
	v_addc_co_u32_e32 v63, vcc, 0, v63, vcc
	s_waitcnt lgkmcnt(0)
	v_cvt_pk_bf16_f32 v60, v60, v61
	ds_read2_b32 v[84:85], v79 offset0:222 offset1:255
	s_waitcnt lgkmcnt(0)
	v_cvt_pk_bf16_f32 v61, v84, v85
	global_store_dwordx4 v[62:63], v[58:61], off
	s_waitcnt lgkmcnt(0)
	s_add_i32 s4, s3, 0xfffff500
	s_cmpk_gt_u32 s4, 0x57f
	s_cbranch_scc0 .LBB0_27
	s_branch .LBB0_28

.LBB0_872:
	s_load_dwordx2 s[6:7], s[44:45], 0x30
	s_lshl_b32 s31, s2, 5
	s_and_b32 s31, s31, 0xfe0
	s_lshl_b32 s33, s31, 2
	s_waitcnt lgkmcnt(0)
	s_add_u32 s6, s6, s33
	s_addc_u32 s7, s7, 0
	v_lshl_add_u64 v[16:17], s[6:7], 0, v[0:1]
	v_lshl_add_u64 v[16:17], v[16:17], 0, s[20:21]
	v_or_b32_e32 v250, s10, v19
	v_mad_u64_u32 v[248:249], s[6:7], v250, s27, v[16:17]
	global_load_dwordx4 v[212:215], v[248:249], off
	v_or_b32_e32 v250, s10, v21
	v_mad_u64_u32 v[248:249], s[6:7], v250, s27, v[16:17]
	global_load_dwordx4 v[216:219], v[248:249], off
	v_or_b32_e32 v250, s10, v22
	v_mad_u64_u32 v[248:249], s[6:7], v250, s27, v[16:17]
	global_load_dwordx4 v[220:223], v[248:249], off
	v_or_b32_e32 v250, s10, v23
	v_mad_u64_u32 v[248:249], s[6:7], v250, s27, v[16:17]
	global_load_dwordx4 v[224:227], v[248:249], off
	v_or_b32_e32 v250, s10, v24
	v_mad_u64_u32 v[248:249], s[6:7], v250, s27, v[16:17]
	global_load_dwordx4 v[228:231], v[248:249], off
	v_mad_u64_u32 v[32:33], s[6:7], v32, s27, v[16:17]
	global_load_dwordx4 v[32:35], v[32:33], off
	s_and_b64 vcc, exec, s[4:5]
	s_waitcnt vmcnt(0)
	v_pk_mul_f32 v[32:33], v[32:33], v[20:21] op_sel_hi:[1,0]
	v_pk_mul_f32 v[34:35], v[34:35], v[20:21] op_sel_hi:[1,0]
	ds_write2_b32 v29, v32, v33 offset1:1
	ds_write2_b32 v29, v34, v35 offset0:2 offset1:3
	v_add_lshl_u32 v32, s10, v9, 2
	s_cbranch_vccnz .LBB0_874
	global_load_dword v18, v32, s[12:13] offset:32
.LBB0_874:
	v_or_b32_e32 v20, s10, v19
	v_mad_u64_u32 v[34:35], s[6:7], v20, s27, v[16:17]
	v_mov_b32_e32 v20, 1.0
	s_and_b64 vcc, exec, s[4:5]
	s_waitcnt vmcnt(0)
	v_pk_mul_f32 v[36:37], v[214:215], v[18:19] op_sel_hi:[1,0]
	v_pk_mul_f32 v[34:35], v[212:213], v[18:19] op_sel_hi:[1,0]
	v_mov_b32_e32 v18, 1.0
	ds_write2_b32 v30, v34, v35 offset1:1
	ds_write2_b32 v30, v36, v37 offset0:2 offset1:3
	s_cbranch_vccnz .LBB0_876
	global_load_dword v18, v32, s[12:13] offset:64
.LBB0_876:
	v_or_b32_e32 v33, s10, v21
	v_mad_u64_u32 v[34:35], s[6:7], v33, s27, v[16:17]
	s_and_b64 vcc, exec, s[4:5]
	s_waitcnt vmcnt(0)
	v_pk_mul_f32 v[34:35], v[216:217], v[18:19] op_sel_hi:[1,0]
	v_pk_mul_f32 v[36:37], v[218:219], v[18:19] op_sel_hi:[1,0]
	ds_write2_b32 v31, v34, v35 offset1:1
	ds_write2_b32 v31, v36, v37 offset0:2 offset1:3
	s_cbranch_vccnz .LBB0_878
	global_load_dword v20, v32, s[12:13] offset:96
.LBB0_878:
	v_or_b32_e32 v18, s10, v22
	v_mad_u64_u32 v[34:35], s[6:7], v18, s27, v[16:17]
	v_add_u32_e32 v33, 0x420, v31
	v_mov_b32_e32 v18, 1.0
	s_and_b64 vcc, exec, s[4:5]
	v_add_u32_e32 v40, 0x428, v31
	s_waitcnt vmcnt(0)
	v_pk_mul_f32 v[36:37], v[222:223], v[20:21] op_sel_hi:[1,0]
	v_pk_mul_f32 v[34:35], v[220:221], v[20:21] op_sel_hi:[1,0]
	v_mov_b32_e32 v20, 1.0
	ds_write2_b32 v33, v34, v35 offset1:1
	ds_write2_b32 v40, v36, v37 offset1:1
	s_cbranch_vccnz .LBB0_880
	global_load_dword v20, v32, s[12:13] offset:128
.LBB0_880:
	v_or_b32_e32 v33, s10, v23
	v_mad_u64_u32 v[34:35], s[6:7], v33, s27, v[16:17]
	v_add_u32_e32 v33, 0x840, v31
	s_and_b64 vcc, exec, s[4:5]
	v_add_u32_e32 v40, 0x848, v31
	s_waitcnt vmcnt(0)
	v_pk_mul_f32 v[34:35], v[224:225], v[20:21] op_sel_hi:[1,0]
	v_pk_mul_f32 v[36:37], v[226:227], v[20:21] op_sel_hi:[1,0]
	ds_write2_b32 v33, v34, v35 offset1:1
	ds_write2_b32 v40, v36, v37 offset1:1
	s_cbranch_vccnz .LBB0_882
	global_load_dword v18, v32, s[12:13] offset:160
.LBB0_882:
	v_or_b32_e32 v20, s10, v24
	v_mad_u64_u32 v[34:35], s[6:7], v20, s27, v[16:17]
	v_add_u32_e32 v20, 0xc60, v31
	s_and_b64 vcc, exec, s[4:5]
	v_add_u32_e32 v33, 0xc68, v31
	s_waitcnt vmcnt(0)
	v_pk_mul_f32 v[34:35], v[228:229], v[18:19] op_sel_hi:[1,0]
	v_pk_mul_f32 v[36:37], v[230:231], v[18:19] op_sel_hi:[1,0]
	ds_write2_b32 v20, v34, v35 offset1:1
	ds_write2_b32 v33, v36, v37 offset1:1
	s_cbranch_vccnz .LBB0_888
	global_load_dword v18, v32, s[12:13] offset:192
	s_branch .LBB0_889

.LBB0_899:
	s_load_dwordx2 s[34:35], s[44:45], 0x128
	s_lshr_b32 s33, s33, 22
	s_mulk_i32 s33, 0x58
	s_sub_i32 s31, s31, s33
	s_lshl_b32 s33, s31, 7
	s_and_b32 s33, s33, 0x3ff80
	s_waitcnt lgkmcnt(0)
	s_add_u32 s34, s34, s33
	s_addc_u32 s35, s35, 0
	v_lshl_add_u64 v[16:17], s[34:35], 0, v[0:1]
	v_or_b32_e32 v250, s10, v19
	v_mad_u64_u32 v[248:249], s[34:35], v250, s29, v[16:17]
	global_load_dwordx4 v[212:215], v[248:249], off
	v_or_b32_e32 v250, s10, v21
	v_mad_u64_u32 v[248:249], s[34:35], v250, s29, v[16:17]
	global_load_dwordx4 v[216:219], v[248:249], off
	v_or_b32_e32 v250, s10, v22
	v_mad_u64_u32 v[248:249], s[34:35], v250, s29, v[16:17]
	global_load_dwordx4 v[220:223], v[248:249], off
	v_or_b32_e32 v250, s10, v23
	v_mad_u64_u32 v[248:249], s[34:35], v250, s29, v[16:17]
	global_load_dwordx4 v[224:227], v[248:249], off
	v_or_b32_e32 v250, s10, v24
	v_mad_u64_u32 v[248:249], s[34:35], v250, s29, v[16:17]
	global_load_dwordx4 v[228:231], v[248:249], off
	v_or_b32_e32 v250, s10, v25
	v_mad_u64_u32 v[248:249], s[34:35], v250, s29, v[16:17]
	global_load_dwordx4 v[232:235], v[248:249], off
	v_or_b32_e32 v250, s10, v26
	v_mad_u64_u32 v[248:249], s[34:35], v250, s29, v[16:17]
	global_load_dwordx4 v[236:239], v[248:249], off
	v_mad_u64_u32 v[32:33], s[34:35], v32, s29, v[16:17]
	global_load_dwordx4 v[32:35], v[32:33], off
	s_and_b64 vcc, exec, s[6:7]
	s_waitcnt vmcnt(0)
	v_pk_mul_f32 v[32:33], v[32:33], v[20:21] op_sel_hi:[1,0]
	v_pk_mul_f32 v[34:35], v[34:35], v[20:21] op_sel_hi:[1,0]
	ds_write2_b32 v29, v32, v33 offset1:1
	ds_write2_b32 v29, v34, v35 offset0:2 offset1:3
	v_add_lshl_u32 v32, v9, s10, 2
	s_cbranch_vccnz .LBB0_901
	global_load_dword v18, v32, s[14:15] offset:32
.LBB0_901:
	v_or_b32_e32 v20, s10, v19
	v_mad_u64_u32 v[34:35], s[34:35], v20, s29, v[16:17]
	v_mov_b32_e32 v20, 1.0
	s_and_b64 vcc, exec, s[6:7]
	s_waitcnt vmcnt(0)
	v_pk_mul_f32 v[36:37], v[214:215], v[18:19] op_sel_hi:[1,0]
	v_pk_mul_f32 v[34:35], v[212:213], v[18:19] op_sel_hi:[1,0]
	v_mov_b32_e32 v18, 1.0
	ds_write2_b32 v30, v34, v35 offset1:1
	ds_write2_b32 v30, v36, v37 offset0:2 offset1:3
	s_cbranch_vccnz .LBB0_903
	global_load_dword v18, v32, s[14:15] offset:64
.LBB0_903:
	v_or_b32_e32 v33, s10, v21
	v_mad_u64_u32 v[34:35], s[34:35], v33, s29, v[16:17]
	s_and_b64 vcc, exec, s[6:7]
	s_waitcnt vmcnt(0)
	v_pk_mul_f32 v[34:35], v[216:217], v[18:19] op_sel_hi:[1,0]
	v_pk_mul_f32 v[36:37], v[218:219], v[18:19] op_sel_hi:[1,0]
	ds_write2_b32 v31, v34, v35 offset1:1
	ds_write2_b32 v31, v36, v37 offset0:2 offset1:3
	s_cbranch_vccnz .LBB0_905
	global_load_dword v20, v32, s[14:15] offset:96
.LBB0_905:
	v_or_b32_e32 v18, s10, v22
	v_mad_u64_u32 v[34:35], s[34:35], v18, s29, v[16:17]
	v_add_u32_e32 v33, 0x420, v31
	v_mov_b32_e32 v18, 1.0
	s_and_b64 vcc, exec, s[6:7]
	v_add_u32_e32 v40, 0x428, v31
	s_waitcnt vmcnt(0)
	v_pk_mul_f32 v[36:37], v[222:223], v[20:21] op_sel_hi:[1,0]
	v_pk_mul_f32 v[34:35], v[220:221], v[20:21] op_sel_hi:[1,0]
	v_mov_b32_e32 v20, 1.0
	ds_write2_b32 v33, v34, v35 offset1:1
	ds_write2_b32 v40, v36, v37 offset1:1
	s_cbranch_vccnz .LBB0_907
	global_load_dword v20, v32, s[14:15] offset:128
.LBB0_907:
	v_or_b32_e32 v33, s10, v23
	v_mad_u64_u32 v[34:35], s[34:35], v33, s29, v[16:17]
	v_add_u32_e32 v33, 0x840, v31
	s_and_b64 vcc, exec, s[6:7]
	v_add_u32_e32 v40, 0x848, v31
	s_waitcnt vmcnt(0)
	v_pk_mul_f32 v[34:35], v[224:225], v[20:21] op_sel_hi:[1,0]
	v_pk_mul_f32 v[36:37], v[226:227], v[20:21] op_sel_hi:[1,0]
	ds_write2_b32 v33, v34, v35 offset1:1
	ds_write2_b32 v40, v36, v37 offset1:1
	s_cbranch_vccnz .LBB0_909
	global_load_dword v18, v32, s[14:15] offset:160
.LBB0_909:
	v_or_b32_e32 v20, s10, v24
	v_mad_u64_u32 v[34:35], s[34:35], v20, s29, v[16:17]
	v_add_u32_e32 v33, 0xc60, v31
	v_mov_b32_e32 v20, 1.0
	s_and_b64 vcc, exec, s[6:7]
	v_add_u32_e32 v40, 0xc68, v31
	s_waitcnt vmcnt(0)
	v_pk_mul_f32 v[36:37], v[230:231], v[18:19] op_sel_hi:[1,0]
	v_pk_mul_f32 v[34:35], v[228:229], v[18:19] op_sel_hi:[1,0]
	v_mov_b32_e32 v18, 1.0
	ds_write2_b32 v33, v34, v35 offset1:1
	ds_write2_b32 v40, v36, v37 offset1:1
	s_cbranch_vccnz .LBB0_911
	global_load_dword v18, v32, s[14:15] offset:192
.LBB0_911:
	v_or_b32_e32 v33, s10, v25
	v_mad_u64_u32 v[34:35], s[34:35], v33, s29, v[16:17]
	v_add_u32_e32 v33, 0x1080, v31
	s_and_b64 vcc, exec, s[6:7]
	v_add_u32_e32 v40, 0x1088, v31
	s_waitcnt vmcnt(0)
	v_pk_mul_f32 v[34:35], v[232:233], v[18:19] op_sel_hi:[1,0]
	v_pk_mul_f32 v[36:37], v[234:235], v[18:19] op_sel_hi:[1,0]
	ds_write2_b32 v33, v34, v35 offset1:1
	ds_write2_b32 v40, v36, v37 offset1:1
	s_cbranch_vccnz .LBB0_913
	global_load_dword v20, v32, s[14:15] offset:224
.LBB0_913:
	v_or_b32_e32 v18, s10, v26
	v_mad_u64_u32 v[16:17], s[34:35], v18, s29, v[16:17]
	v_add_u32_e32 v18, 0x14a0, v31
	v_add_u32_e32 v36, 0x14a8, v31
	s_lshl_b32 s31, s31, 5
	s_lshl_b32 s10, s10, 1
	s_and_b32 s31, 0xffff, s31
	v_lshl_add_u64 v[40:41], v[10:11], 0, s[10:11]
	s_lshl_b32 s10, s31, 1
	s_and_b32 s31, s31, 0x60
	s_and_b32 s10, s10, 0x1f00
	s_or_b32 s10, s10, s31
	v_mov_b32_e32 v37, v1
	s_waitcnt vmcnt(0)
	v_pk_mul_f32 v[32:33], v[236:237], v[20:21] op_sel_hi:[1,0]
	v_pk_mul_f32 v[16:17], v[238:239], v[20:21] op_sel_hi:[1,0]
	ds_write2_b32 v18, v32, v33 offset1:1
	ds_write2_b32 v36, v16, v17 offset1:1
	s_waitcnt lgkmcnt(0)
	ds_read2_b32 v[16:17], v27 offset1:33
	s_waitcnt lgkmcnt(0)
	v_cvt_pk_bf16_f32 v32, v16, v17
	ds_read2_b32 v[16:17], v27 offset0:66 offset1:99
	s_waitcnt lgkmcnt(0)
	v_cvt_pk_bf16_f32 v33, v16, v17
	ds_read2_b32 v[16:17], v27 offset0:132 offset1:165
	v_or_b32_e32 v18, s10, v9
	s_waitcnt lgkmcnt(0)
	v_cvt_pk_bf16_f32 v34, v16, v17
	ds_read2_b32 v[16:17], v27 offset0:198 offset1:231
	v_lshlrev_b32_e32 v36, 11, v18
	s_waitcnt lgkmcnt(0)
	v_cvt_pk_bf16_f32 v35, v16, v17
	ds_read2_b32 v[16:17], v27 offset0:8 offset1:41
	v_lshl_add_u64 v[36:37], v[40:41], 0, v[36:37]
	global_store_dwordx4 v[36:37], v[32:35], off
	v_or_b32_e32 v18, s10, v19
	v_mov_b32_e32 v37, v1
	s_waitcnt lgkmcnt(0)
	v_cvt_pk_bf16_f32 v32, v16, v17
	ds_read2_b32 v[16:17], v27 offset0:74 offset1:107
	s_waitcnt lgkmcnt(0)
	v_cvt_pk_bf16_f32 v33, v16, v17
	ds_read2_b32 v[16:17], v27 offset0:140 offset1:173
	s_waitcnt lgkmcnt(0)
	v_cvt_pk_bf16_f32 v34, v16, v17
	ds_read2_b32 v[16:17], v27 offset0:206 offset1:239
	v_lshlrev_b32_e32 v36, 11, v18
	s_waitcnt lgkmcnt(0)
	v_cvt_pk_bf16_f32 v35, v16, v17
	ds_read2_b32 v[16:17], v27 offset0:16 offset1:49
	v_lshl_add_u64 v[36:37], v[40:41], 0, v[36:37]
	global_store_dwordx4 v[36:37], v[32:35], off
	v_or_b32_e32 v18, s10, v21
	v_mov_b32_e32 v37, v1
	s_waitcnt lgkmcnt(0)
	v_cvt_pk_bf16_f32 v32, v16, v17
	ds_read2_b32 v[16:17], v27 offset0:82 offset1:115
	s_waitcnt lgkmcnt(0)
	v_cvt_pk_bf16_f32 v33, v16, v17
	ds_read2_b32 v[16:17], v27 offset0:148 offset1:181
	s_waitcnt lgkmcnt(0)
	v_cvt_pk_bf16_f32 v34, v16, v17
	ds_read2_b32 v[16:17], v27 offset0:214 offset1:247
	v_lshlrev_b32_e32 v36, 11, v18
	s_waitcnt lgkmcnt(0)
	v_cvt_pk_bf16_f32 v35, v16, v17
	ds_read2_b32 v[16:17], v27 offset0:24 offset1:57
	v_lshl_add_u64 v[36:37], v[40:41], 0, v[36:37]
	global_store_dwordx4 v[36:37], v[32:35], off
	v_or_b32_e32 v18, s10, v22
	v_mov_b32_e32 v37, v1
	s_waitcnt lgkmcnt(0)
	v_cvt_pk_bf16_f32 v32, v16, v17
	ds_read2_b32 v[16:17], v27 offset0:90 offset1:123
	s_waitcnt lgkmcnt(0)
	v_cvt_pk_bf16_f32 v33, v16, v17
	ds_read2_b32 v[16:17], v27 offset0:156 offset1:189
	s_waitcnt lgkmcnt(0)
	v_cvt_pk_bf16_f32 v34, v16, v17
	ds_read2_b32 v[16:17], v27 offset0:222 offset1:255
	v_lshlrev_b32_e32 v36, 11, v18
	s_waitcnt lgkmcnt(0)
	v_cvt_pk_bf16_f32 v35, v16, v17
	v_lshl_add_u64 v[16:17], v[40:41], 0, v[36:37]
	global_store_dwordx4 v[16:17], v[32:35], off
	s_waitcnt lgkmcnt(0)

.LBB0_917:
	s_load_dwordx2 s[34:35], s[44:45], 0x130
	s_lshr_b32 s33, s33, 22
	s_mulk_i32 s33, 0x58
	s_sub_i32 s31, s31, s33
	s_lshl_b32 s33, s31, 7
	s_and_b32 s33, s33, 0x3ff80
	s_waitcnt lgkmcnt(0)
	s_add_u32 s34, s34, s33
	s_addc_u32 s35, s35, 0
	v_lshl_add_u64 v[16:17], s[34:35], 0, v[0:1]
	v_or_b32_e32 v250, s10, v19
	v_mad_u64_u32 v[248:249], s[34:35], v250, s29, v[16:17]
	global_load_dwordx4 v[212:215], v[248:249], off
	v_or_b32_e32 v250, s10, v21
	v_mad_u64_u32 v[248:249], s[34:35], v250, s29, v[16:17]
	global_load_dwordx4 v[216:219], v[248:249], off
	v_or_b32_e32 v250, s10, v22
	v_mad_u64_u32 v[248:249], s[34:35], v250, s29, v[16:17]
	global_load_dwordx4 v[220:223], v[248:249], off
	v_or_b32_e32 v250, s10, v23
	v_mad_u64_u32 v[248:249], s[34:35], v250, s29, v[16:17]
	global_load_dwordx4 v[224:227], v[248:249], off
	v_or_b32_e32 v250, s10, v24
	v_mad_u64_u32 v[248:249], s[34:35], v250, s29, v[16:17]
	global_load_dwordx4 v[228:231], v[248:249], off
	v_or_b32_e32 v250, s10, v25
	v_mad_u64_u32 v[248:249], s[34:35], v250, s29, v[16:17]
	global_load_dwordx4 v[232:235], v[248:249], off
	v_or_b32_e32 v250, s10, v26
	v_mad_u64_u32 v[248:249], s[34:35], v250, s29, v[16:17]
	global_load_dwordx4 v[236:239], v[248:249], off
	v_mad_u64_u32 v[32:33], s[34:35], v32, s29, v[16:17]
	global_load_dwordx4 v[32:35], v[32:33], off
	s_and_b64 vcc, exec, s[6:7]
	s_waitcnt vmcnt(0)
	v_pk_mul_f32 v[32:33], v[32:33], v[20:21] op_sel_hi:[1,0]
	v_pk_mul_f32 v[34:35], v[34:35], v[20:21] op_sel_hi:[1,0]
	ds_write2_b32 v29, v32, v33 offset1:1
	ds_write2_b32 v29, v34, v35 offset0:2 offset1:3
	v_add_lshl_u32 v32, v9, s10, 2
	s_cbranch_vccnz .LBB0_919
	global_load_dword v18, v32, s[14:15] offset:32

.LBB0_931:
	v_or_b32_e32 v18, s10, v26
	v_mad_u64_u32 v[16:17], s[6:7], v18, s29, v[16:17]
	s_lshl_b32 s6, s31, 5
	s_and_b32 s6, 0xffff, s6
	s_lshl_b32 s7, s6, 1
	v_add_u32_e32 v18, 0x14a0, v31
	s_and_b32 s6, s6, 0x60
	s_and_b32 s7, s7, 0x1f00
	v_add_u32_e32 v36, 0x14a8, v31
	s_or_b32 s6, s7, s6
	s_lshl_b32 s10, s10, 1
	v_mov_b32_e32 v37, v1
	v_lshl_add_u64 v[40:41], v[10:11], 0, s[10:11]
	s_waitcnt vmcnt(0)
	v_pk_mul_f32 v[32:33], v[236:237], v[20:21] op_sel_hi:[1,0]
	v_pk_mul_f32 v[16:17], v[238:239], v[20:21] op_sel_hi:[1,0]
	ds_write2_b32 v18, v32, v33 offset1:1
	ds_write2_b32 v36, v16, v17 offset1:1
	s_waitcnt lgkmcnt(0)
	v_or_b32_e32 v18, s6, v9
	v_lshlrev_b32_e32 v36, 11, v18
	ds_read2_b32 v[16:17], v27 offset1:33
	v_lshl_add_u64 v[36:37], v[40:41], 0, v[36:37]
	s_waitcnt lgkmcnt(0)
	v_cvt_pk_bf16_f32 v32, v16, v17
	ds_read2_b32 v[16:17], v27 offset0:66 offset1:99
	v_add_co_u32_e32 v36, vcc, s30, v36
	s_waitcnt lgkmcnt(0)
	v_cvt_pk_bf16_f32 v33, v16, v17
	ds_read2_b32 v[16:17], v27 offset0:132 offset1:165
	v_addc_co_u32_e32 v37, vcc, 0, v37, vcc
	v_or_b32_e32 v18, s6, v19
	s_waitcnt lgkmcnt(0)
	v_cvt_pk_bf16_f32 v34, v16, v17
	ds_read2_b32 v[16:17], v27 offset0:198 offset1:231
	s_waitcnt lgkmcnt(0)
	v_cvt_pk_bf16_f32 v35, v16, v17
	global_store_dwordx4 v[36:37], v[32:35], off
	v_mov_b32_e32 v37, v1
	v_lshlrev_b32_e32 v36, 11, v18
	ds_read2_b32 v[16:17], v27 offset0:8 offset1:41
	v_lshl_add_u64 v[36:37], v[40:41], 0, v[36:37]
	s_waitcnt lgkmcnt(0)
	v_cvt_pk_bf16_f32 v32, v16, v17
	ds_read2_b32 v[16:17], v27 offset0:74 offset1:107
	v_add_co_u32_e32 v36, vcc, s30, v36
	s_waitcnt lgkmcnt(0)
	v_cvt_pk_bf16_f32 v33, v16, v17
	ds_read2_b32 v[16:17], v27 offset0:140 offset1:173
	v_addc_co_u32_e32 v37, vcc, 0, v37, vcc
	v_or_b32_e32 v18, s6, v21
	s_waitcnt lgkmcnt(0)
	v_cvt_pk_bf16_f32 v34, v16, v17
	ds_read2_b32 v[16:17], v27 offset0:206 offset1:239
	s_waitcnt lgkmcnt(0)
	v_cvt_pk_bf16_f32 v35, v16, v17
	global_store_dwordx4 v[36:37], v[32:35], off
	v_mov_b32_e32 v37, v1
	v_lshlrev_b32_e32 v36, 11, v18
	ds_read2_b32 v[16:17], v27 offset0:16 offset1:49
	v_lshl_add_u64 v[36:37], v[40:41], 0, v[36:37]
	s_waitcnt lgkmcnt(0)
	v_cvt_pk_bf16_f32 v32, v16, v17
	ds_read2_b32 v[16:17], v27 offset0:82 offset1:115
	v_add_co_u32_e32 v36, vcc, s30, v36
	s_waitcnt lgkmcnt(0)
	v_cvt_pk_bf16_f32 v33, v16, v17
	ds_read2_b32 v[16:17], v27 offset0:148 offset1:181
	v_addc_co_u32_e32 v37, vcc, 0, v37, vcc
	v_or_b32_e32 v18, s6, v22
	s_waitcnt lgkmcnt(0)
	v_cvt_pk_bf16_f32 v34, v16, v17
	ds_read2_b32 v[16:17], v27 offset0:214 offset1:247
	s_waitcnt lgkmcnt(0)
	v_cvt_pk_bf16_f32 v35, v16, v17
	global_store_dwordx4 v[36:37], v[32:35], off
	v_mov_b32_e32 v37, v1
	v_lshlrev_b32_e32 v36, 11, v18
	ds_read2_b32 v[16:17], v27 offset0:24 offset1:57
	v_lshl_add_u64 v[36:37], v[40:41], 0, v[36:37]
	s_waitcnt lgkmcnt(0)
	v_cvt_pk_bf16_f32 v32, v16, v17
	ds_read2_b32 v[16:17], v27 offset0:90 offset1:123
	v_add_co_u32_e32 v36, vcc, 0x40000, v36
	s_waitcnt lgkmcnt(0)
	v_cvt_pk_bf16_f32 v33, v16, v17
	ds_read2_b32 v[16:17], v27 offset0:156 offset1:189
	v_addc_co_u32_e32 v37, vcc, 0, v37, vcc
	s_waitcnt lgkmcnt(0)
	v_cvt_pk_bf16_f32 v34, v16, v17
	ds_read2_b32 v[16:17], v27 offset0:222 offset1:255
	s_waitcnt lgkmcnt(0)
	v_cvt_pk_bf16_f32 v35, v16, v17
	global_store_dwordx4 v[36:37], v[32:35], off
	s_waitcnt lgkmcnt(0)

.LBB0_1702:
	s_load_dwordx2 s[48:49], s[10:11], 0x10
	s_lshr_b32 s37, s37, 22
	s_mulk_i32 s37, 0x58
	s_sub_i32 s37, s1, s37
	s_lshl_b32 s50, s37, 7
	s_and_b32 s50, s50, 0x3ff80
	s_waitcnt lgkmcnt(0)
	s_add_u32 s48, s48, s50
	s_addc_u32 s49, s49, 0
	v_lshlrev_b32_e32 v2, 2, v0
	v_lshl_add_u64 v[56:57], s[48:49], 0, v[2:3]
	v_lshl_add_u64 v[56:57], v[56:57], 0, s[26:27]
	v_or_b32_e32 v250, s8, v62
	v_mad_u64_u32 v[248:249], s[48:49], v250, s3, v[56:57]
	global_load_dwordx4 v[212:215], v[248:249], off
	v_or_b32_e32 v250, s8, v64
	v_mad_u64_u32 v[248:249], s[48:49], v250, s3, v[56:57]
	global_load_dwordx4 v[216:219], v[248:249], off
	v_or_b32_e32 v250, s8, v66
	v_mad_u64_u32 v[248:249], s[48:49], v250, s3, v[56:57]
	global_load_dwordx4 v[220:223], v[248:249], off
	v_or_b32_e32 v250, s8, v68
	v_mad_u64_u32 v[248:249], s[48:49], v250, s3, v[56:57]
	global_load_dwordx4 v[224:227], v[248:249], off
	v_or_b32_e32 v250, s8, v70
	v_mad_u64_u32 v[248:249], s[48:49], v250, s3, v[56:57]
	global_load_dwordx4 v[228:231], v[248:249], off
	v_or_b32_e32 v250, s8, v72
	v_mad_u64_u32 v[248:249], s[48:49], v250, s3, v[56:57]
	global_load_dwordx4 v[232:235], v[248:249], off
	v_or_b32_e32 v250, s8, v73
	v_mad_u64_u32 v[248:249], s[48:49], v250, s3, v[56:57]
	global_load_dwordx4 v[236:239], v[248:249], off
	v_mad_u64_u32 v[76:77], s[48:49], v76, s3, v[56:57]
	global_load_dwordx4 v[76:79], v[76:77], off
	v_add_u32_e32 v2, v59, v61
	s_and_b64 vcc, exec, s[4:5]
	s_waitcnt vmcnt(0)
	v_pk_mul_f32 v[76:77], v[76:77], v[60:61] op_sel_hi:[1,0]
	v_pk_mul_f32 v[78:79], v[78:79], v[60:61] op_sel_hi:[1,0]
	ds_write2_b32 v2, v76, v77 offset1:1
	ds_write2_b32 v2, v78, v79 offset0:2 offset1:3
	v_or_b32_e32 v2, s8, v62
	s_cbranch_vccnz .LBB0_1704
	v_lshlrev_b32_e32 v58, 2, v2
	global_load_dword v58, v58, s[12:13]
.LBB0_1704:
	v_mad_u64_u32 v[76:77], s[48:49], v2, s3, v[56:57]
	v_add_u32_e32 v80, v59, v63
	v_or_b32_e32 v60, s8, v64
	v_mov_b32_e32 v2, 1.0
	s_and_b64 vcc, exec, s[4:5]
	s_waitcnt vmcnt(0)
	v_pk_mul_f32 v[78:79], v[214:215], v[58:59] op_sel_hi:[1,0]
	v_pk_mul_f32 v[76:77], v[212:213], v[58:59] op_sel_hi:[1,0]
	v_mov_b32_e32 v58, 1.0
	ds_write2_b32 v80, v76, v77 offset1:1
	ds_write2_b32 v80, v78, v79 offset0:2 offset1:3
	s_cbranch_vccnz .LBB0_1706
	v_lshlrev_b32_e32 v58, 2, v60
	global_load_dword v58, v58, s[12:13]
.LBB0_1706:
	v_mad_u64_u32 v[76:77], s[48:49], v60, s3, v[56:57]
	v_add_u32_e32 v60, v59, v65
	s_and_b64 vcc, exec, s[4:5]
	s_waitcnt vmcnt(0)
	v_pk_mul_f32 v[78:79], v[218:219], v[58:59] op_sel_hi:[1,0]
	v_pk_mul_f32 v[76:77], v[216:217], v[58:59] op_sel_hi:[1,0]
	v_or_b32_e32 v58, s8, v66
	ds_write2_b32 v60, v76, v77 offset1:1
	ds_write2_b32 v60, v78, v79 offset0:2 offset1:3
	s_cbranch_vccnz .LBB0_1708
	v_lshlrev_b32_e32 v2, 2, v58
	global_load_dword v2, v2, s[12:13]
.LBB0_1708:
	v_mad_u64_u32 v[76:77], s[48:49], v58, s3, v[56:57]
	v_add_u32_e32 v80, v59, v67
	v_or_b32_e32 v60, s8, v68
	v_mov_b32_e32 v58, 1.0
	s_and_b64 vcc, exec, s[4:5]
	s_waitcnt vmcnt(0)
	v_pk_mul_f32 v[78:79], v[222:223], v[2:3] op_sel_hi:[1,0]
	v_pk_mul_f32 v[76:77], v[220:221], v[2:3] op_sel_hi:[1,0]
	v_mov_b32_e32 v2, 1.0
	ds_write2_b32 v80, v76, v77 offset1:1
	ds_write2_b32 v80, v78, v79 offset0:2 offset1:3
	s_cbranch_vccnz .LBB0_1710
	v_lshlrev_b32_e32 v2, 2, v60
	global_load_dword v2, v2, s[12:13]
.LBB0_1710:
	v_mad_u64_u32 v[76:77], s[48:49], v60, s3, v[56:57]
	v_add_u32_e32 v60, v59, v69
	s_and_b64 vcc, exec, s[4:5]
	s_waitcnt vmcnt(0)
	v_pk_mul_f32 v[78:79], v[226:227], v[2:3] op_sel_hi:[1,0]
	v_pk_mul_f32 v[76:77], v[224:225], v[2:3] op_sel_hi:[1,0]
	v_or_b32_e32 v2, s8, v70
	ds_write2_b32 v60, v76, v77 offset1:1
	ds_write2_b32 v60, v78, v79 offset0:2 offset1:3
	s_cbranch_vccnz .LBB0_1712
	v_lshlrev_b32_e32 v58, 2, v2
	global_load_dword v58, v58, s[12:13]
.LBB0_1712:
	v_mad_u64_u32 v[76:77], s[48:49], v2, s3, v[56:57]
	v_add_u32_e32 v60, v59, v71
	v_or_b32_e32 v76, s8, v72
	v_mov_b32_e32 v2, 1.0
	s_and_b64 vcc, exec, s[4:5]
	s_waitcnt vmcnt(0)
	v_pk_mul_f32 v[80:81], v[230:231], v[58:59] op_sel_hi:[1,0]
	v_pk_mul_f32 v[78:79], v[228:229], v[58:59] op_sel_hi:[1,0]
	v_mov_b32_e32 v58, 1.0
	ds_write2_b32 v60, v78, v79 offset1:1
	ds_write2_b32 v60, v80, v81 offset0:2 offset1:3
	s_cbranch_vccnz .LBB0_1714
	v_lshlrev_b32_e32 v58, 2, v76
	global_load_dword v58, v58, s[12:13]
.LBB0_1714:
	v_mad_u64_u32 v[76:77], s[48:49], v76, s3, v[56:57]
	v_add_u32_e32 v80, 0x420, v60
	s_and_b64 vcc, exec, s[4:5]
	v_add_u32_e32 v81, 0x428, v60
	s_waitcnt vmcnt(0)
	v_pk_mul_f32 v[78:79], v[234:235], v[58:59] op_sel_hi:[1,0]
	v_pk_mul_f32 v[76:77], v[232:233], v[58:59] op_sel_hi:[1,0]
	v_or_b32_e32 v58, s8, v73
	ds_write2_b32 v80, v76, v77 offset1:1
	ds_write2_b32 v81, v78, v79 offset1:1
	s_cbranch_vccnz .LBB0_1716
	v_lshlrev_b32_e32 v2, 2, v58
	global_load_dword v2, v2, s[12:13]
.LBB0_1716:
	v_mad_u64_u32 v[56:57], s[48:49], v58, s3, v[56:57]
	v_add_u32_e32 v58, 0x840, v60
	v_add_u32_e32 v60, 0x848, v60
	s_lshl_b32 s37, s37, 5
	s_lshl_b32 s8, s8, 1
	s_and_b32 s37, 0xffff, s37
	v_lshl_add_u64 v[80:81], v[4:5], 0, s[8:9]
	s_lshl_b32 s8, s37, 1
	s_and_b32 s37, s37, 0x60
	s_and_b32 s8, s8, 0x1f00
	s_or_b32 s8, s8, s37
	s_waitcnt vmcnt(0)
	v_pk_mul_f32 v[76:77], v[236:237], v[2:3] op_sel_hi:[1,0]
	v_pk_mul_f32 v[56:57], v[238:239], v[2:3] op_sel_hi:[1,0]
	ds_write2_b32 v58, v76, v77 offset1:1
	ds_write2_b32 v60, v56, v57 offset1:1
	s_waitcnt lgkmcnt(0)
	ds_read2_b32 v[56:57], v74 offset1:33
	s_waitcnt lgkmcnt(0)
	v_cvt_pk_bf16_f32 v76, v56, v57
	ds_read2_b32 v[56:57], v74 offset0:66 offset1:99
	s_waitcnt lgkmcnt(0)
	v_cvt_pk_bf16_f32 v77, v56, v57
	ds_read2_b32 v[56:57], v74 offset0:132 offset1:165
	v_or_b32_e32 v2, s8, v1
	s_waitcnt lgkmcnt(0)
	v_cvt_pk_bf16_f32 v78, v56, v57
	ds_read2_b32 v[56:57], v74 offset0:198 offset1:231
	v_lshlrev_b32_e32 v2, 11, v2
	s_waitcnt lgkmcnt(0)
	v_cvt_pk_bf16_f32 v79, v56, v57
	ds_read2_b32 v[56:57], v74 offset0:8 offset1:41
	v_lshl_add_u64 v[82:83], v[80:81], 0, v[2:3]
	global_store_dwordx4 v[82:83], v[76:79], off
	v_or_b32_e32 v2, s8, v62
	v_lshlrev_b32_e32 v2, 11, v2
	s_waitcnt lgkmcnt(0)
	v_cvt_pk_bf16_f32 v76, v56, v57
	ds_read2_b32 v[56:57], v74 offset0:74 offset1:107
	s_waitcnt lgkmcnt(0)
	v_cvt_pk_bf16_f32 v77, v56, v57
	ds_read2_b32 v[56:57], v74 offset0:140 offset1:173
	s_waitcnt lgkmcnt(0)
	v_cvt_pk_bf16_f32 v78, v56, v57
	ds_read2_b32 v[56:57], v74 offset0:206 offset1:239
	s_waitcnt lgkmcnt(0)
	v_cvt_pk_bf16_f32 v79, v56, v57
	ds_read2_b32 v[56:57], v74 offset0:16 offset1:49
	v_lshl_add_u64 v[82:83], v[80:81], 0, v[2:3]
	global_store_dwordx4 v[82:83], v[76:79], off
	v_or_b32_e32 v2, s8, v64
	v_lshlrev_b32_e32 v2, 11, v2
	s_waitcnt lgkmcnt(0)
	v_cvt_pk_bf16_f32 v76, v56, v57
	ds_read2_b32 v[56:57], v74 offset0:82 offset1:115
	s_waitcnt lgkmcnt(0)
	v_cvt_pk_bf16_f32 v77, v56, v57
	ds_read2_b32 v[56:57], v74 offset0:148 offset1:181
	s_waitcnt lgkmcnt(0)
	v_cvt_pk_bf16_f32 v78, v56, v57
	ds_read2_b32 v[56:57], v74 offset0:214 offset1:247
	s_waitcnt lgkmcnt(0)
	v_cvt_pk_bf16_f32 v79, v56, v57
	ds_read2_b32 v[56:57], v74 offset0:24 offset1:57
	v_lshl_add_u64 v[82:83], v[80:81], 0, v[2:3]
	global_store_dwordx4 v[82:83], v[76:79], off
	v_or_b32_e32 v2, s8, v66
	v_lshlrev_b32_e32 v2, 11, v2
	s_waitcnt lgkmcnt(0)
	v_cvt_pk_bf16_f32 v76, v56, v57
	ds_read2_b32 v[56:57], v74 offset0:90 offset1:123
	s_waitcnt lgkmcnt(0)
	v_cvt_pk_bf16_f32 v77, v56, v57
	ds_read2_b32 v[56:57], v74 offset0:156 offset1:189
	s_waitcnt lgkmcnt(0)
	v_cvt_pk_bf16_f32 v78, v56, v57
	ds_read2_b32 v[56:57], v74 offset0:222 offset1:255
	s_waitcnt lgkmcnt(0)
	v_cvt_pk_bf16_f32 v79, v56, v57
	v_lshl_add_u64 v[56:57], v[80:81], 0, v[2:3]
	global_store_dwordx4 v[56:57], v[76:79], off
	s_waitcnt lgkmcnt(0)
	s_add_i32 s37, s1, 0xfffffa80
	s_cmpk_gt_u32 s37, 0x57f
	s_cbranch_scc0 .LBB0_1739

.LBB0_1722:
	s_load_dwordx2 s[48:49], s[10:11], 0x30
	s_lshl_b32 s37, s1, 5
	s_and_b32 s37, s37, 0x7e0
	s_lshl_b32 s50, s37, 2
	v_lshlrev_b32_e32 v2, 2, v0
	s_waitcnt lgkmcnt(0)
	s_add_u32 s48, s48, s50
	s_addc_u32 s49, s49, 0
	v_lshl_add_u64 v[56:57], s[48:49], 0, v[2:3]
	v_lshl_add_u64 v[56:57], v[56:57], 0, s[28:29]
	v_or_b32_e32 v250, s8, v62
	v_mad_u64_u32 v[248:249], s[48:49], v250, s36, v[56:57]
	global_load_dwordx4 v[212:215], v[248:249], off
	v_or_b32_e32 v250, s8, v64
	v_mad_u64_u32 v[248:249], s[48:49], v250, s36, v[56:57]
	global_load_dwordx4 v[216:219], v[248:249], off
	v_or_b32_e32 v250, s8, v66
	v_mad_u64_u32 v[248:249], s[48:49], v250, s36, v[56:57]
	global_load_dwordx4 v[220:223], v[248:249], off
	v_or_b32_e32 v250, s8, v68
	v_mad_u64_u32 v[248:249], s[48:49], v250, s36, v[56:57]
	global_load_dwordx4 v[224:227], v[248:249], off
	v_or_b32_e32 v250, s8, v70
	v_mad_u64_u32 v[248:249], s[48:49], v250, s36, v[56:57]
	global_load_dwordx4 v[228:231], v[248:249], off
	v_or_b32_e32 v250, s8, v72
	v_mad_u64_u32 v[248:249], s[48:49], v250, s36, v[56:57]
	global_load_dwordx4 v[232:235], v[248:249], off
	v_or_b32_e32 v250, s8, v73
	v_mad_u64_u32 v[248:249], s[48:49], v250, s36, v[56:57]
	global_load_dwordx4 v[236:239], v[248:249], off
	v_mad_u64_u32 v[76:77], s[48:49], v76, s36, v[56:57]
	global_load_dwordx4 v[76:79], v[76:77], off
	v_add_u32_e32 v2, v59, v61
	s_and_b64 vcc, exec, s[4:5]
	s_waitcnt vmcnt(0)
	v_pk_mul_f32 v[76:77], v[76:77], v[60:61] op_sel_hi:[1,0]
	v_pk_mul_f32 v[78:79], v[78:79], v[60:61] op_sel_hi:[1,0]
	ds_write2_b32 v2, v76, v77 offset1:1
	ds_write2_b32 v2, v78, v79 offset0:2 offset1:3
	v_or_b32_e32 v2, s8, v62
	s_cbranch_vccnz .LBB0_1724
	v_lshlrev_b32_e32 v58, 2, v2
	global_load_dword v58, v58, s[14:15]
.LBB0_1724:
	v_mad_u64_u32 v[76:77], s[48:49], v2, s36, v[56:57]
	v_add_u32_e32 v80, v59, v63
	v_or_b32_e32 v60, s8, v64
	v_mov_b32_e32 v2, 1.0
	s_and_b64 vcc, exec, s[4:5]
	s_waitcnt vmcnt(0)
	v_pk_mul_f32 v[78:79], v[214:215], v[58:59] op_sel_hi:[1,0]
	v_pk_mul_f32 v[76:77], v[212:213], v[58:59] op_sel_hi:[1,0]
	v_mov_b32_e32 v58, 1.0
	ds_write2_b32 v80, v76, v77 offset1:1
	ds_write2_b32 v80, v78, v79 offset0:2 offset1:3
	s_cbranch_vccnz .LBB0_1726
	v_lshlrev_b32_e32 v58, 2, v60
	global_load_dword v58, v58, s[14:15]
.LBB0_1726:
	v_mad_u64_u32 v[76:77], s[48:49], v60, s36, v[56:57]
	v_add_u32_e32 v60, v59, v65
	s_and_b64 vcc, exec, s[4:5]
	s_waitcnt vmcnt(0)
	v_pk_mul_f32 v[78:79], v[218:219], v[58:59] op_sel_hi:[1,0]
	v_pk_mul_f32 v[76:77], v[216:217], v[58:59] op_sel_hi:[1,0]
	v_or_b32_e32 v58, s8, v66
	ds_write2_b32 v60, v76, v77 offset1:1
	ds_write2_b32 v60, v78, v79 offset0:2 offset1:3
	s_cbranch_vccnz .LBB0_1728
	v_lshlrev_b32_e32 v2, 2, v58
	global_load_dword v2, v2, s[14:15]
.LBB0_1728:
	v_mad_u64_u32 v[76:77], s[48:49], v58, s36, v[56:57]
	v_add_u32_e32 v80, v59, v67
	v_or_b32_e32 v60, s8, v68
	v_mov_b32_e32 v58, 1.0
	s_and_b64 vcc, exec, s[4:5]
	s_waitcnt vmcnt(0)
	v_pk_mul_f32 v[78:79], v[222:223], v[2:3] op_sel_hi:[1,0]
	v_pk_mul_f32 v[76:77], v[220:221], v[2:3] op_sel_hi:[1,0]
	v_mov_b32_e32 v2, 1.0
	ds_write2_b32 v80, v76, v77 offset1:1
	ds_write2_b32 v80, v78, v79 offset0:2 offset1:3
	s_cbranch_vccnz .LBB0_1730
	v_lshlrev_b32_e32 v2, 2, v60
	global_load_dword v2, v2, s[14:15]
.LBB0_1730:
	v_mad_u64_u32 v[76:77], s[48:49], v60, s36, v[56:57]
	v_add_u32_e32 v60, v59, v69
	s_and_b64 vcc, exec, s[4:5]
	s_waitcnt vmcnt(0)
	v_pk_mul_f32 v[78:79], v[226:227], v[2:3] op_sel_hi:[1,0]
	v_pk_mul_f32 v[76:77], v[224:225], v[2:3] op_sel_hi:[1,0]
	v_or_b32_e32 v2, s8, v70
	ds_write2_b32 v60, v76, v77 offset1:1
	ds_write2_b32 v60, v78, v79 offset0:2 offset1:3
	s_cbranch_vccnz .LBB0_1732
	v_lshlrev_b32_e32 v58, 2, v2
	global_load_dword v58, v58, s[14:15]
.LBB0_1732:
	v_mad_u64_u32 v[76:77], s[48:49], v2, s36, v[56:57]
	v_add_u32_e32 v60, v59, v71
	v_or_b32_e32 v76, s8, v72
	v_mov_b32_e32 v2, 1.0
	s_and_b64 vcc, exec, s[4:5]
	s_waitcnt vmcnt(0)
	v_pk_mul_f32 v[80:81], v[230:231], v[58:59] op_sel_hi:[1,0]
	v_pk_mul_f32 v[78:79], v[228:229], v[58:59] op_sel_hi:[1,0]
	v_mov_b32_e32 v58, 1.0
	ds_write2_b32 v60, v78, v79 offset1:1
	ds_write2_b32 v60, v80, v81 offset0:2 offset1:3
	s_cbranch_vccnz .LBB0_1734
	v_lshlrev_b32_e32 v58, 2, v76
	global_load_dword v58, v58, s[14:15]
.LBB0_1734:
	v_mad_u64_u32 v[76:77], s[48:49], v76, s36, v[56:57]
	v_add_u32_e32 v80, 0x420, v60
	s_and_b64 vcc, exec, s[4:5]
	v_add_u32_e32 v81, 0x428, v60
	s_waitcnt vmcnt(0)
	v_pk_mul_f32 v[78:79], v[234:235], v[58:59] op_sel_hi:[1,0]
	v_pk_mul_f32 v[76:77], v[232:233], v[58:59] op_sel_hi:[1,0]
	v_or_b32_e32 v58, s8, v73
	ds_write2_b32 v80, v76, v77 offset1:1
	ds_write2_b32 v81, v78, v79 offset1:1
	s_cbranch_vccnz .LBB0_1736
	v_lshlrev_b32_e32 v2, 2, v58
	global_load_dword v2, v2, s[14:15]
.LBB0_1736:
	v_mad_u64_u32 v[56:57], s[48:49], v58, s36, v[56:57]
	v_add_u32_e32 v58, 0x840, v60
	v_add_u32_e32 v60, 0x848, v60
	s_and_b32 s37, 0xffff, s37
	s_lshl_b32 s8, s8, 1
	v_lshl_add_u64 v[80:81], v[8:9], 0, s[8:9]
	s_waitcnt vmcnt(0)
	v_pk_mul_f32 v[76:77], v[236:237], v[2:3] op_sel_hi:[1,0]
	v_pk_mul_f32 v[56:57], v[238:239], v[2:3] op_sel_hi:[1,0]
	ds_write2_b32 v58, v76, v77 offset1:1
	ds_write2_b32 v60, v56, v57 offset1:1
	s_waitcnt lgkmcnt(0)
	ds_read2_b32 v[56:57], v74 offset1:33
	s_waitcnt lgkmcnt(0)
	v_cvt_pk_bf16_f32 v76, v56, v57
	ds_read2_b32 v[56:57], v74 offset0:66 offset1:99
	s_waitcnt lgkmcnt(0)
	v_cvt_pk_bf16_f32 v77, v56, v57
	ds_read2_b32 v[56:57], v74 offset0:132 offset1:165
	v_or_b32_e32 v2, s37, v1
	s_waitcnt lgkmcnt(0)
	v_cvt_pk_bf16_f32 v78, v56, v57
	ds_read2_b32 v[56:57], v74 offset0:198 offset1:231
	v_lshlrev_b32_e32 v2, 11, v2
	s_waitcnt lgkmcnt(0)
	v_cvt_pk_bf16_f32 v79, v56, v57
	ds_read2_b32 v[56:57], v74 offset0:8 offset1:41
	v_lshl_add_u64 v[82:83], v[80:81], 0, v[2:3]
	global_store_dwordx4 v[82:83], v[76:79], off
	v_or_b32_e32 v2, s37, v62
	v_lshlrev_b32_e32 v2, 11, v2
	s_waitcnt lgkmcnt(0)
	v_cvt_pk_bf16_f32 v76, v56, v57
	ds_read2_b32 v[56:57], v74 offset0:74 offset1:107
	s_waitcnt lgkmcnt(0)
	v_cvt_pk_bf16_f32 v77, v56, v57
	ds_read2_b32 v[56:57], v74 offset0:140 offset1:173
	s_waitcnt lgkmcnt(0)
	v_cvt_pk_bf16_f32 v78, v56, v57
	ds_read2_b32 v[56:57], v74 offset0:206 offset1:239
	s_waitcnt lgkmcnt(0)
	v_cvt_pk_bf16_f32 v79, v56, v57
	ds_read2_b32 v[56:57], v74 offset0:16 offset1:49
	v_lshl_add_u64 v[82:83], v[80:81], 0, v[2:3]
	global_store_dwordx4 v[82:83], v[76:79], off
	v_or_b32_e32 v2, s37, v64
	v_lshlrev_b32_e32 v2, 11, v2
	s_waitcnt lgkmcnt(0)
	v_cvt_pk_bf16_f32 v76, v56, v57
	ds_read2_b32 v[56:57], v74 offset0:82 offset1:115
	s_waitcnt lgkmcnt(0)
	v_cvt_pk_bf16_f32 v77, v56, v57
	ds_read2_b32 v[56:57], v74 offset0:148 offset1:181
	s_waitcnt lgkmcnt(0)
	v_cvt_pk_bf16_f32 v78, v56, v57
	ds_read2_b32 v[56:57], v74 offset0:214 offset1:247
	s_waitcnt lgkmcnt(0)
	v_cvt_pk_bf16_f32 v79, v56, v57
	ds_read2_b32 v[56:57], v74 offset0:24 offset1:57
	v_lshl_add_u64 v[82:83], v[80:81], 0, v[2:3]
	global_store_dwordx4 v[82:83], v[76:79], off
	v_or_b32_e32 v2, s37, v66
	v_lshlrev_b32_e32 v2, 11, v2
	s_waitcnt lgkmcnt(0)
	v_cvt_pk_bf16_f32 v76, v56, v57
	ds_read2_b32 v[56:57], v74 offset0:90 offset1:123
	s_waitcnt lgkmcnt(0)
	v_cvt_pk_bf16_f32 v77, v56, v57
	ds_read2_b32 v[56:57], v74 offset0:156 offset1:189
	s_waitcnt lgkmcnt(0)
	v_cvt_pk_bf16_f32 v78, v56, v57
	ds_read2_b32 v[56:57], v74 offset0:222 offset1:255
	s_waitcnt lgkmcnt(0)
	v_cvt_pk_bf16_f32 v79, v56, v57
	v_lshl_add_u64 v[56:57], v[80:81], 0, v[2:3]
	global_store_dwordx4 v[56:57], v[76:79], off
	s_waitcnt lgkmcnt(0)
	s_and_b32 s37, s1, 0xffffffe0
	s_cmpk_lt_i32 s37, 0x14a0
	s_mov_b64 s[48:49], -1
	s_cbranch_scc0 .LBB0_1757

.LBB0_1741:
	s_load_dwordx2 s[50:51], s[10:11], 0x18
	s_lshr_b32 s48, s48, 22
	s_mulk_i32 s48, 0x58
	s_sub_i32 s37, s37, s48
	s_lshl_b32 s48, s37, 7
	s_and_b32 s48, s48, 0x3ff80
	s_waitcnt lgkmcnt(0)
	s_add_u32 s48, s50, s48
	s_addc_u32 s49, s51, 0
	v_lshlrev_b32_e32 v2, 2, v0
	v_lshl_add_u64 v[56:57], s[48:49], 0, v[2:3]
	v_lshl_add_u64 v[56:57], v[56:57], 0, s[26:27]
	v_or_b32_e32 v250, s8, v62
	v_mad_u64_u32 v[248:249], s[48:49], v250, s3, v[56:57]
	global_load_dwordx4 v[212:215], v[248:249], off
	v_or_b32_e32 v250, s8, v64
	v_mad_u64_u32 v[248:249], s[48:49], v250, s3, v[56:57]
	global_load_dwordx4 v[216:219], v[248:249], off
	v_or_b32_e32 v250, s8, v66
	v_mad_u64_u32 v[248:249], s[48:49], v250, s3, v[56:57]
	global_load_dwordx4 v[220:223], v[248:249], off
	v_or_b32_e32 v250, s8, v68
	v_mad_u64_u32 v[248:249], s[48:49], v250, s3, v[56:57]
	global_load_dwordx4 v[224:227], v[248:249], off
	v_or_b32_e32 v250, s8, v70
	v_mad_u64_u32 v[248:249], s[48:49], v250, s3, v[56:57]
	global_load_dwordx4 v[228:231], v[248:249], off
	v_or_b32_e32 v250, s8, v72
	v_mad_u64_u32 v[248:249], s[48:49], v250, s3, v[56:57]
	global_load_dwordx4 v[232:235], v[248:249], off
	v_or_b32_e32 v250, s8, v73
	v_mad_u64_u32 v[248:249], s[48:49], v250, s3, v[56:57]
	global_load_dwordx4 v[236:239], v[248:249], off
	v_mad_u64_u32 v[76:77], s[48:49], v76, s3, v[56:57]
	global_load_dwordx4 v[76:79], v[76:77], off
	v_add_u32_e32 v2, v59, v61
	s_and_b64 vcc, exec, s[4:5]
	s_waitcnt vmcnt(0)
	v_pk_mul_f32 v[76:77], v[76:77], v[60:61] op_sel_hi:[1,0]
	v_pk_mul_f32 v[78:79], v[78:79], v[60:61] op_sel_hi:[1,0]
	ds_write2_b32 v2, v76, v77 offset1:1
	ds_write2_b32 v2, v78, v79 offset0:2 offset1:3
	v_or_b32_e32 v2, s8, v62
	s_cbranch_vccnz .LBB0_1743
	v_lshlrev_b32_e32 v58, 2, v2
	global_load_dword v58, v58, s[12:13]

.LBB0_1755:
	v_mad_u64_u32 v[56:57], s[4:5], v58, s3, v[56:57]
	s_lshl_b32 s4, s37, 5
	v_add_u32_e32 v58, 0x840, v60
	s_and_b32 s4, 0xffff, s4
	v_add_u32_e32 v60, 0x848, v60
	s_lshl_b32 s5, s4, 1
	s_and_b32 s4, s4, 0x60
	s_and_b32 s5, s5, 0x1f00
	s_or_b32 s4, s5, s4
	s_lshl_b32 s8, s8, 1
	v_lshl_add_u64 v[80:81], v[4:5], 0, s[8:9]
	s_waitcnt vmcnt(0)
	v_pk_mul_f32 v[76:77], v[236:237], v[2:3] op_sel_hi:[1,0]
	v_pk_mul_f32 v[56:57], v[238:239], v[2:3] op_sel_hi:[1,0]
	ds_write2_b32 v58, v76, v77 offset1:1
	ds_write2_b32 v60, v56, v57 offset1:1
	s_waitcnt lgkmcnt(0)
	ds_read2_b32 v[56:57], v74 offset1:33
	v_or_b32_e32 v2, s4, v1
	s_waitcnt lgkmcnt(0)
	v_cvt_pk_bf16_f32 v76, v56, v57
	ds_read2_b32 v[56:57], v74 offset0:66 offset1:99
	v_lshlrev_b32_e32 v2, 11, v2
	s_waitcnt lgkmcnt(0)
	v_cvt_pk_bf16_f32 v77, v56, v57
	ds_read2_b32 v[56:57], v74 offset0:132 offset1:165
	v_lshl_add_u64 v[82:83], v[80:81], 0, v[2:3]
	s_waitcnt lgkmcnt(0)
	v_cvt_pk_bf16_f32 v78, v56, v57
	ds_read2_b32 v[56:57], v74 offset0:198 offset1:231
	v_add_co_u32_e32 v82, vcc, s33, v82
	s_waitcnt lgkmcnt(0)
	v_cvt_pk_bf16_f32 v79, v56, v57
	ds_read2_b32 v[56:57], v74 offset0:8 offset1:41
	v_addc_co_u32_e32 v83, vcc, 0, v83, vcc
	v_or_b32_e32 v2, s4, v62
	global_store_dwordx4 v[82:83], v[76:79], off
	v_lshlrev_b32_e32 v2, 11, v2
	v_lshl_add_u64 v[82:83], v[80:81], 0, v[2:3]
	s_waitcnt lgkmcnt(0)
	v_cvt_pk_bf16_f32 v76, v56, v57
	ds_read2_b32 v[56:57], v74 offset0:74 offset1:107
	s_waitcnt lgkmcnt(0)
	v_cvt_pk_bf16_f32 v77, v56, v57
	ds_read2_b32 v[56:57], v74 offset0:140 offset1:173
	s_waitcnt lgkmcnt(0)
	v_cvt_pk_bf16_f32 v78, v56, v57
	ds_read2_b32 v[56:57], v74 offset0:206 offset1:239
	v_add_co_u32_e32 v82, vcc, s33, v82
	s_waitcnt lgkmcnt(0)
	v_cvt_pk_bf16_f32 v79, v56, v57
	ds_read2_b32 v[56:57], v74 offset0:16 offset1:49
	v_addc_co_u32_e32 v83, vcc, 0, v83, vcc
	v_or_b32_e32 v2, s4, v64
	global_store_dwordx4 v[82:83], v[76:79], off
	v_lshlrev_b32_e32 v2, 11, v2
	v_lshl_add_u64 v[82:83], v[80:81], 0, v[2:3]
	s_waitcnt lgkmcnt(0)
	v_cvt_pk_bf16_f32 v76, v56, v57
	ds_read2_b32 v[56:57], v74 offset0:82 offset1:115
	s_waitcnt lgkmcnt(0)
	v_cvt_pk_bf16_f32 v77, v56, v57
	ds_read2_b32 v[56:57], v74 offset0:148 offset1:181
	v_or_b32_e32 v2, s4, v66
	s_waitcnt lgkmcnt(0)
	v_cvt_pk_bf16_f32 v78, v56, v57
	ds_read2_b32 v[56:57], v74 offset0:214 offset1:247
	v_add_co_u32_e32 v82, vcc, s33, v82
	v_lshlrev_b32_e32 v2, 11, v2
	s_waitcnt lgkmcnt(0)
	v_cvt_pk_bf16_f32 v79, v56, v57
	ds_read2_b32 v[56:57], v74 offset0:24 offset1:57
	v_addc_co_u32_e32 v83, vcc, 0, v83, vcc
	v_lshl_add_u64 v[80:81], v[80:81], 0, v[2:3]
	global_store_dwordx4 v[82:83], v[76:79], off
	v_add_co_u32_e32 v80, vcc, 0x40000, v80
	s_waitcnt lgkmcnt(0)
	v_cvt_pk_bf16_f32 v76, v56, v57
	ds_read2_b32 v[56:57], v74 offset0:90 offset1:123
	s_waitcnt lgkmcnt(0)
	v_cvt_pk_bf16_f32 v77, v56, v57
	ds_read2_b32 v[56:57], v74 offset0:156 offset1:189
	v_addc_co_u32_e32 v81, vcc, 0, v81, vcc
	s_waitcnt lgkmcnt(0)
	v_cvt_pk_bf16_f32 v78, v56, v57
	ds_read2_b32 v[56:57], v74 offset0:222 offset1:255
	s_waitcnt lgkmcnt(0)
	v_cvt_pk_bf16_f32 v79, v56, v57
	global_store_dwordx4 v[80:81], v[76:79], off
	s_waitcnt lgkmcnt(0)
	s_add_i32 s4, s1, 0xfffff500
	s_cmpk_gt_u32 s4, 0x57f
	s_cbranch_scc0 .LBB0_1718
	s_branch .LBB0_1719

.LBB0_2581:
	s_load_dwordx2 s[36:37], s[44:45], 0x30
	s_lshl_b32 s7, s2, 5
	s_and_b32 s7, s7, 0xfe0
	s_lshl_b32 s10, s7, 2
	s_waitcnt lgkmcnt(0)
	s_add_u32 s36, s36, s10
	s_addc_u32 s37, s37, 0
	v_lshl_add_u64 v[16:17], s[36:37], 0, v[0:1]
	v_lshl_add_u64 v[16:17], v[16:17], 0, s[20:21]
	v_or_b32_e32 v250, s6, v21
	v_mad_u64_u32 v[248:249], s[36:37], v250, s31, v[16:17]
	global_load_dwordx4 v[212:215], v[248:249], off
	v_or_b32_e32 v250, s6, v22
	v_mad_u64_u32 v[248:249], s[36:37], v250, s31, v[16:17]
	global_load_dwordx4 v[216:219], v[248:249], off
	v_or_b32_e32 v250, s6, v24
	v_mad_u64_u32 v[248:249], s[36:37], v250, s31, v[16:17]
	global_load_dwordx4 v[220:223], v[248:249], off
	v_or_b32_e32 v250, s6, v25
	v_mad_u64_u32 v[248:249], s[36:37], v250, s31, v[16:17]
	global_load_dwordx4 v[224:227], v[248:249], off
	v_or_b32_e32 v250, s6, v26
	v_mad_u64_u32 v[248:249], s[36:37], v250, s31, v[16:17]
	global_load_dwordx4 v[228:231], v[248:249], off
	v_or_b32_e32 v250, s6, v27
	v_mad_u64_u32 v[248:249], s[36:37], v250, s31, v[16:17]
	global_load_dwordx4 v[232:235], v[248:249], off
	v_or_b32_e32 v250, s6, v28
	v_mad_u64_u32 v[248:249], s[36:37], v250, s31, v[16:17]
	global_load_dwordx4 v[236:239], v[248:249], off
	v_mad_u64_u32 v[34:35], s[36:37], v33, s31, v[16:17]
	global_load_dwordx4 v[34:37], v[34:35], off
	s_and_b64 vcc, exec, s[4:5]
	s_waitcnt vmcnt(0)
	v_pk_mul_f32 v[36:37], v[36:37], v[20:21] op_sel_hi:[1,0]
	v_pk_mul_f32 v[34:35], v[34:35], v[20:21] op_sel_hi:[1,0]
	v_or_b32_e32 v20, s6, v21
	ds_write2_b32 v31, v34, v35 offset1:1
	ds_write2_b32 v31, v36, v37 offset0:2 offset1:3
	s_cbranch_vccnz .LBB0_2583
	v_lshlrev_b32_e32 v18, 2, v20
	global_load_dword v18, v18, s[12:13]
.LBB0_2583:
	v_mad_u64_u32 v[34:35], s[36:37], v20, s31, v[16:17]
	v_or_b32_e32 v33, s6, v22
	v_mov_b32_e32 v20, 1.0
	s_and_b64 vcc, exec, s[4:5]
	s_waitcnt vmcnt(0)
	v_pk_mul_f32 v[36:37], v[214:215], v[18:19] op_sel_hi:[1,0]
	v_pk_mul_f32 v[34:35], v[212:213], v[18:19] op_sel_hi:[1,0]
	v_mov_b32_e32 v18, 1.0
	ds_write2_b32 v32, v34, v35 offset1:1
	ds_write2_b32 v32, v36, v37 offset0:2 offset1:3
	s_cbranch_vccnz .LBB0_2585
	v_lshlrev_b32_e32 v18, 2, v33
	global_load_dword v18, v18, s[12:13]
.LBB0_2585:
	v_mad_u64_u32 v[34:35], s[36:37], v33, s31, v[16:17]
	v_add_u32_e32 v33, v19, v23
	s_and_b64 vcc, exec, s[4:5]
	s_waitcnt vmcnt(0)
	v_pk_mul_f32 v[36:37], v[218:219], v[18:19] op_sel_hi:[1,0]
	v_pk_mul_f32 v[34:35], v[216:217], v[18:19] op_sel_hi:[1,0]
	v_or_b32_e32 v18, s6, v24
	ds_write2_b32 v33, v34, v35 offset1:1
	ds_write2_b32 v33, v36, v37 offset0:2 offset1:3
	s_cbranch_vccnz .LBB0_2587
	v_lshlrev_b32_e32 v20, 2, v18
	global_load_dword v20, v20, s[12:13]
.LBB0_2587:
	v_mad_u64_u32 v[34:35], s[36:37], v18, s31, v[16:17]
	v_add_u32_e32 v35, 0x420, v33
	v_or_b32_e32 v34, s6, v25
	v_mov_b32_e32 v18, 1.0
	s_and_b64 vcc, exec, s[4:5]
	v_add_u32_e32 v44, 0x428, v33
	s_waitcnt vmcnt(0)
	v_pk_mul_f32 v[36:37], v[222:223], v[20:21] op_sel_hi:[1,0]
	v_pk_mul_f32 v[40:41], v[220:221], v[20:21] op_sel_hi:[1,0]
	v_mov_b32_e32 v20, 1.0
	ds_write2_b32 v35, v40, v41 offset1:1
	ds_write2_b32 v44, v36, v37 offset1:1
	s_cbranch_vccnz .LBB0_2589
	v_lshlrev_b32_e32 v20, 2, v34
	global_load_dword v20, v20, s[12:13]
.LBB0_2589:
	v_mad_u64_u32 v[34:35], s[36:37], v34, s31, v[16:17]
	v_add_u32_e32 v40, 0x840, v33
	s_and_b64 vcc, exec, s[4:5]
	v_add_u32_e32 v41, 0x848, v33
	s_waitcnt vmcnt(0)
	v_pk_mul_f32 v[36:37], v[226:227], v[20:21] op_sel_hi:[1,0]
	v_pk_mul_f32 v[34:35], v[224:225], v[20:21] op_sel_hi:[1,0]
	v_or_b32_e32 v20, s6, v26
	ds_write2_b32 v40, v34, v35 offset1:1
	ds_write2_b32 v41, v36, v37 offset1:1
	s_cbranch_vccnz .LBB0_2591
	v_lshlrev_b32_e32 v18, 2, v20
	global_load_dword v18, v18, s[12:13]
.LBB0_2591:
	v_mad_u64_u32 v[34:35], s[36:37], v20, s31, v[16:17]
	v_add_u32_e32 v35, 0xc60, v33
	v_or_b32_e32 v34, s6, v27
	v_mov_b32_e32 v20, 1.0
	s_and_b64 vcc, exec, s[4:5]
	v_add_u32_e32 v44, 0xc68, v33
	s_waitcnt vmcnt(0)
	v_pk_mul_f32 v[36:37], v[230:231], v[18:19] op_sel_hi:[1,0]
	v_pk_mul_f32 v[40:41], v[228:229], v[18:19] op_sel_hi:[1,0]
	v_mov_b32_e32 v18, 1.0
	ds_write2_b32 v35, v40, v41 offset1:1
	ds_write2_b32 v44, v36, v37 offset1:1
	s_cbranch_vccnz .LBB0_2593
	v_lshlrev_b32_e32 v18, 2, v34
	global_load_dword v18, v18, s[12:13]
.LBB0_2593:
	v_mad_u64_u32 v[34:35], s[36:37], v34, s31, v[16:17]
	v_add_u32_e32 v40, 0x1080, v33
	s_and_b64 vcc, exec, s[4:5]
	v_add_u32_e32 v41, 0x1088, v33
	s_waitcnt vmcnt(0)
	v_pk_mul_f32 v[36:37], v[234:235], v[18:19] op_sel_hi:[1,0]
	v_pk_mul_f32 v[34:35], v[232:233], v[18:19] op_sel_hi:[1,0]
	v_or_b32_e32 v18, s6, v28
	ds_write2_b32 v40, v34, v35 offset1:1
	ds_write2_b32 v41, v36, v37 offset1:1
	s_cbranch_vccnz .LBB0_2595
	v_lshlrev_b32_e32 v20, 2, v18
	global_load_dword v20, v20, s[12:13]
.LBB0_2595:
	v_mad_u64_u32 v[16:17], s[36:37], v18, s31, v[16:17]
	v_add_u32_e32 v18, 0x14a0, v33
	s_and_b32 s7, 0xffff, s7
	v_add_u32_e32 v33, 0x14a8, v33
	s_lshl_b32 s10, s6, 1
	s_lshr_b32 s36, s7, 4
	v_lshl_add_u64 v[42:43], v[2:3], 0, s[10:11]
	s_lshr_b32 s6, s7, 6
	s_lshl_b32 s10, s7, 2
	s_and_b32 s7, s7, 0x60
	s_and_b32 s36, s36, 0x80
	s_and_b32 s6, s6, 16
	s_or_b32 s37, s36, s7
	s_and_b32 s10, s10, 0xe00
	s_or_b32 s37, s37, s6
	s_or_b32 s37, s37, s10
	v_mov_b32_e32 v41, v1
	v_mov_b32_e32 v45, v1
	s_waitcnt vmcnt(0)
	v_pk_mul_f32 v[34:35], v[236:237], v[20:21] op_sel_hi:[1,0]
	v_pk_mul_f32 v[16:17], v[238:239], v[20:21] op_sel_hi:[1,0]
	ds_write2_b32 v18, v34, v35 offset1:1
	ds_write2_b32 v33, v16, v17 offset1:1
	s_waitcnt lgkmcnt(0)
	ds_read2_b32 v[16:17], v29 offset1:33
	s_waitcnt lgkmcnt(0)
	v_cvt_pk_bf16_f32 v34, v16, v17
	ds_read2_b32 v[16:17], v29 offset0:66 offset1:99
	s_waitcnt lgkmcnt(0)
	v_cvt_pk_bf16_f32 v35, v16, v17
	ds_read2_b32 v[16:17], v29 offset0:132 offset1:165
	v_or_b32_e32 v18, s37, v9
	s_waitcnt lgkmcnt(0)
	v_cvt_pk_bf16_f32 v36, v16, v17
	ds_read2_b32 v[16:17], v29 offset0:198 offset1:231
	v_lshlrev_b32_e32 v40, 11, v18
	s_waitcnt lgkmcnt(0)
	v_cvt_pk_bf16_f32 v37, v16, v17
	ds_read2_b32 v[16:17], v29 offset0:8 offset1:41
	v_lshl_add_u64 v[40:41], v[42:43], 0, v[40:41]
	global_store_dwordx4 v[40:41], v[34:37], off
	v_or_b32_e32 v18, s37, v21
	v_lshlrev_b32_e32 v44, 11, v18
	s_waitcnt lgkmcnt(0)
	v_cvt_pk_bf16_f32 v34, v16, v17
	ds_read2_b32 v[16:17], v29 offset0:74 offset1:107
	s_waitcnt lgkmcnt(0)
	v_cvt_pk_bf16_f32 v35, v16, v17
	ds_read2_b32 v[16:17], v29 offset0:140 offset1:173
	s_waitcnt lgkmcnt(0)
	v_cvt_pk_bf16_f32 v36, v16, v17
	ds_read2_b32 v[16:17], v29 offset0:206 offset1:239
	v_or_b32_e32 v18, s7, v30
	s_waitcnt lgkmcnt(0)
	v_cvt_pk_bf16_f32 v37, v16, v17
	ds_read2_b32 v[16:17], v29 offset0:16 offset1:49
	v_lshl_add_u64 v[44:45], v[42:43], 0, v[44:45]
	v_or_b32_e32 v18, s36, v18
	global_store_dwordx4 v[44:45], v[34:37], off
	v_add_co_u32_e32 v40, vcc, s33, v40
	s_waitcnt lgkmcnt(0)
	v_cvt_pk_bf16_f32 v34, v16, v17
	ds_read2_b32 v[16:17], v29 offset0:82 offset1:115
	v_or_b32_e32 v18, s6, v18
	s_waitcnt lgkmcnt(0)
	v_cvt_pk_bf16_f32 v35, v16, v17
	ds_read2_b32 v[16:17], v29 offset0:148 offset1:181
	v_addc_co_u32_e32 v41, vcc, 0, v41, vcc
	v_or_b32_e32 v18, s10, v18
	s_waitcnt lgkmcnt(0)
	v_cvt_pk_bf16_f32 v36, v16, v17
	ds_read2_b32 v[16:17], v29 offset0:214 offset1:247
	s_waitcnt lgkmcnt(0)
	v_cvt_pk_bf16_f32 v37, v16, v17
	global_store_dwordx4 v[40:41], v[34:37], off
	v_mov_b32_e32 v41, v1
	v_lshlrev_b32_e32 v40, 11, v18
	ds_read2_b32 v[16:17], v29 offset0:24 offset1:57
	v_lshl_add_u64 v[40:41], v[42:43], 0, v[40:41]
	s_waitcnt lgkmcnt(0)
	v_cvt_pk_bf16_f32 v34, v16, v17
	ds_read2_b32 v[16:17], v29 offset0:90 offset1:123
	v_add_co_u32_e32 v40, vcc, 0x80000, v40
	s_waitcnt lgkmcnt(0)
	v_cvt_pk_bf16_f32 v35, v16, v17
	ds_read2_b32 v[16:17], v29 offset0:156 offset1:189
	v_addc_co_u32_e32 v41, vcc, 0, v41, vcc
	s_waitcnt lgkmcnt(0)
	v_cvt_pk_bf16_f32 v36, v16, v17
	ds_read2_b32 v[16:17], v29 offset0:222 offset1:255
	s_waitcnt lgkmcnt(0)
	v_cvt_pk_bf16_f32 v37, v16, v17
	global_store_dwordx4 v[40:41], v[34:37], off
	s_waitcnt lgkmcnt(0)
	s_and_b32 s36, s2, 0xfffffe00
	s_cmpk_lt_i32 s36, 0xa00
	s_mov_b64 s[6:7], -1
	s_cbranch_scc0 .LBB0_2598

.LBB0_2606:
	s_load_dwordx2 s[48:49], s[44:45], 0x128
	s_lshr_b32 s37, s37, 22
	s_mulk_i32 s37, 0x58
	s_sub_i32 s36, s36, s37
	s_lshl_b32 s37, s36, 7
	s_and_b32 s37, s37, 0x3ff80
	s_waitcnt lgkmcnt(0)
	s_add_u32 s48, s48, s37
	s_addc_u32 s49, s49, 0
	v_lshl_add_u64 v[16:17], s[48:49], 0, v[0:1]
	v_lshl_add_u64 v[16:17], v[16:17], 0, s[22:23]
	v_or_b32_e32 v250, s10, v21
	v_mad_u64_u32 v[248:249], s[48:49], v250, s34, v[16:17]
	global_load_dwordx4 v[212:215], v[248:249], off
	v_or_b32_e32 v250, s10, v22
	v_mad_u64_u32 v[248:249], s[48:49], v250, s34, v[16:17]
	global_load_dwordx4 v[216:219], v[248:249], off
	v_or_b32_e32 v250, s10, v24
	v_mad_u64_u32 v[248:249], s[48:49], v250, s34, v[16:17]
	global_load_dwordx4 v[220:223], v[248:249], off
	v_or_b32_e32 v250, s10, v25
	v_mad_u64_u32 v[248:249], s[48:49], v250, s34, v[16:17]
	global_load_dwordx4 v[224:227], v[248:249], off
	v_or_b32_e32 v250, s10, v26
	v_mad_u64_u32 v[248:249], s[48:49], v250, s34, v[16:17]
	global_load_dwordx4 v[228:231], v[248:249], off
	v_or_b32_e32 v250, s10, v27
	v_mad_u64_u32 v[248:249], s[48:49], v250, s34, v[16:17]
	global_load_dwordx4 v[232:235], v[248:249], off
	v_or_b32_e32 v250, s10, v28
	v_mad_u64_u32 v[248:249], s[48:49], v250, s34, v[16:17]
	global_load_dwordx4 v[236:239], v[248:249], off
	v_mad_u64_u32 v[34:35], s[48:49], v33, s34, v[16:17]
	global_load_dwordx4 v[34:37], v[34:35], off
	s_and_b64 vcc, exec, s[6:7]
	s_waitcnt vmcnt(0)
	v_pk_mul_f32 v[36:37], v[36:37], v[20:21] op_sel_hi:[1,0]
	v_pk_mul_f32 v[34:35], v[34:35], v[20:21] op_sel_hi:[1,0]
	v_or_b32_e32 v20, s10, v21
	ds_write2_b32 v31, v34, v35 offset1:1
	ds_write2_b32 v31, v36, v37 offset0:2 offset1:3
	s_cbranch_vccnz .LBB0_2608
	v_lshlrev_b32_e32 v18, 2, v20
	global_load_dword v18, v18, s[14:15]
.LBB0_2608:
	v_mad_u64_u32 v[34:35], s[48:49], v20, s34, v[16:17]
	v_or_b32_e32 v33, s10, v22
	v_mov_b32_e32 v20, 1.0
	s_and_b64 vcc, exec, s[6:7]
	s_waitcnt vmcnt(0)
	v_pk_mul_f32 v[36:37], v[214:215], v[18:19] op_sel_hi:[1,0]
	v_pk_mul_f32 v[34:35], v[212:213], v[18:19] op_sel_hi:[1,0]
	v_mov_b32_e32 v18, 1.0
	ds_write2_b32 v32, v34, v35 offset1:1
	ds_write2_b32 v32, v36, v37 offset0:2 offset1:3
	s_cbranch_vccnz .LBB0_2610
	v_lshlrev_b32_e32 v18, 2, v33
	global_load_dword v18, v18, s[14:15]
.LBB0_2610:
	v_mad_u64_u32 v[34:35], s[48:49], v33, s34, v[16:17]
	v_add_u32_e32 v33, v19, v23
	s_and_b64 vcc, exec, s[6:7]
	s_waitcnt vmcnt(0)
	v_pk_mul_f32 v[36:37], v[218:219], v[18:19] op_sel_hi:[1,0]
	v_pk_mul_f32 v[34:35], v[216:217], v[18:19] op_sel_hi:[1,0]
	v_or_b32_e32 v18, s10, v24
	ds_write2_b32 v33, v34, v35 offset1:1
	ds_write2_b32 v33, v36, v37 offset0:2 offset1:3
	s_cbranch_vccnz .LBB0_2612
	v_lshlrev_b32_e32 v20, 2, v18
	global_load_dword v20, v20, s[14:15]
.LBB0_2612:
	v_mad_u64_u32 v[34:35], s[48:49], v18, s34, v[16:17]
	v_add_u32_e32 v35, 0x420, v33
	v_or_b32_e32 v34, s10, v25
	v_mov_b32_e32 v18, 1.0
	s_and_b64 vcc, exec, s[6:7]
	v_add_u32_e32 v44, 0x428, v33
	s_waitcnt vmcnt(0)
	v_pk_mul_f32 v[36:37], v[222:223], v[20:21] op_sel_hi:[1,0]
	v_pk_mul_f32 v[40:41], v[220:221], v[20:21] op_sel_hi:[1,0]
	v_mov_b32_e32 v20, 1.0
	ds_write2_b32 v35, v40, v41 offset1:1
	ds_write2_b32 v44, v36, v37 offset1:1
	s_cbranch_vccnz .LBB0_2614
	v_lshlrev_b32_e32 v20, 2, v34
	global_load_dword v20, v20, s[14:15]
.LBB0_2614:
	v_mad_u64_u32 v[34:35], s[48:49], v34, s34, v[16:17]
	v_add_u32_e32 v40, 0x840, v33
	s_and_b64 vcc, exec, s[6:7]
	v_add_u32_e32 v41, 0x848, v33
	s_waitcnt vmcnt(0)
	v_pk_mul_f32 v[36:37], v[226:227], v[20:21] op_sel_hi:[1,0]
	v_pk_mul_f32 v[34:35], v[224:225], v[20:21] op_sel_hi:[1,0]
	v_or_b32_e32 v20, s10, v26
	ds_write2_b32 v40, v34, v35 offset1:1
	ds_write2_b32 v41, v36, v37 offset1:1
	s_cbranch_vccnz .LBB0_2616
	v_lshlrev_b32_e32 v18, 2, v20
	global_load_dword v18, v18, s[14:15]
.LBB0_2616:
	v_mad_u64_u32 v[34:35], s[48:49], v20, s34, v[16:17]
	v_add_u32_e32 v35, 0xc60, v33
	v_or_b32_e32 v34, s10, v27
	v_mov_b32_e32 v20, 1.0
	s_and_b64 vcc, exec, s[6:7]
	v_add_u32_e32 v44, 0xc68, v33
	s_waitcnt vmcnt(0)
	v_pk_mul_f32 v[36:37], v[230:231], v[18:19] op_sel_hi:[1,0]
	v_pk_mul_f32 v[40:41], v[228:229], v[18:19] op_sel_hi:[1,0]
	v_mov_b32_e32 v18, 1.0
	ds_write2_b32 v35, v40, v41 offset1:1
	ds_write2_b32 v44, v36, v37 offset1:1
	s_cbranch_vccnz .LBB0_2618
	v_lshlrev_b32_e32 v18, 2, v34
	global_load_dword v18, v18, s[14:15]
.LBB0_2618:
	v_mad_u64_u32 v[34:35], s[48:49], v34, s34, v[16:17]
	v_add_u32_e32 v40, 0x1080, v33
	s_and_b64 vcc, exec, s[6:7]
	v_add_u32_e32 v41, 0x1088, v33
	s_waitcnt vmcnt(0)
	v_pk_mul_f32 v[36:37], v[234:235], v[18:19] op_sel_hi:[1,0]
	v_pk_mul_f32 v[34:35], v[232:233], v[18:19] op_sel_hi:[1,0]
	v_or_b32_e32 v18, s10, v28
	ds_write2_b32 v40, v34, v35 offset1:1
	ds_write2_b32 v41, v36, v37 offset1:1
	s_cbranch_vccnz .LBB0_2620
	v_lshlrev_b32_e32 v20, 2, v18
	global_load_dword v20, v20, s[14:15]
.LBB0_2620:
	v_mad_u64_u32 v[16:17], s[48:49], v18, s34, v[16:17]
	v_add_u32_e32 v18, 0x14a0, v33
	v_add_u32_e32 v33, 0x14a8, v33
	s_lshl_b32 s36, s36, 5
	s_lshl_b32 s10, s10, 1
	s_and_b32 s36, 0xffff, s36
	v_lshl_add_u64 v[42:43], v[10:11], 0, s[10:11]
	s_lshl_b32 s10, s36, 1
	s_and_b32 s36, s36, 0x60
	s_and_b32 s10, s10, 0x1f00
	s_or_b32 s10, s10, s36
	v_mov_b32_e32 v41, v1
	s_waitcnt vmcnt(0)
	v_pk_mul_f32 v[34:35], v[236:237], v[20:21] op_sel_hi:[1,0]
	v_pk_mul_f32 v[16:17], v[238:239], v[20:21] op_sel_hi:[1,0]
	ds_write2_b32 v18, v34, v35 offset1:1
	ds_write2_b32 v33, v16, v17 offset1:1
	s_waitcnt lgkmcnt(0)
	ds_read2_b32 v[16:17], v29 offset1:33
	s_waitcnt lgkmcnt(0)
	v_cvt_pk_bf16_f32 v34, v16, v17
	ds_read2_b32 v[16:17], v29 offset0:66 offset1:99
	s_waitcnt lgkmcnt(0)
	v_cvt_pk_bf16_f32 v35, v16, v17
	ds_read2_b32 v[16:17], v29 offset0:132 offset1:165
	v_or_b32_e32 v18, s10, v9
	s_waitcnt lgkmcnt(0)
	v_cvt_pk_bf16_f32 v36, v16, v17
	ds_read2_b32 v[16:17], v29 offset0:198 offset1:231
	v_lshlrev_b32_e32 v40, 11, v18
	s_waitcnt lgkmcnt(0)
	v_cvt_pk_bf16_f32 v37, v16, v17
	ds_read2_b32 v[16:17], v29 offset0:8 offset1:41
	v_lshl_add_u64 v[40:41], v[42:43], 0, v[40:41]
	global_store_dwordx4 v[40:41], v[34:37], off
	v_or_b32_e32 v18, s10, v21
	v_mov_b32_e32 v41, v1
	s_waitcnt lgkmcnt(0)
	v_cvt_pk_bf16_f32 v34, v16, v17
	ds_read2_b32 v[16:17], v29 offset0:74 offset1:107
	s_waitcnt lgkmcnt(0)
	v_cvt_pk_bf16_f32 v35, v16, v17
	ds_read2_b32 v[16:17], v29 offset0:140 offset1:173
	s_waitcnt lgkmcnt(0)
	v_cvt_pk_bf16_f32 v36, v16, v17
	ds_read2_b32 v[16:17], v29 offset0:206 offset1:239
	v_lshlrev_b32_e32 v40, 11, v18
	s_waitcnt lgkmcnt(0)
	v_cvt_pk_bf16_f32 v37, v16, v17
	ds_read2_b32 v[16:17], v29 offset0:16 offset1:49
	v_lshl_add_u64 v[40:41], v[42:43], 0, v[40:41]
	global_store_dwordx4 v[40:41], v[34:37], off
	v_or_b32_e32 v18, s10, v22
	v_mov_b32_e32 v41, v1
	s_waitcnt lgkmcnt(0)
	v_cvt_pk_bf16_f32 v34, v16, v17
	ds_read2_b32 v[16:17], v29 offset0:82 offset1:115
	s_waitcnt lgkmcnt(0)
	v_cvt_pk_bf16_f32 v35, v16, v17
	ds_read2_b32 v[16:17], v29 offset0:148 offset1:181
	s_waitcnt lgkmcnt(0)
	v_cvt_pk_bf16_f32 v36, v16, v17
	ds_read2_b32 v[16:17], v29 offset0:214 offset1:247
	v_lshlrev_b32_e32 v40, 11, v18
	s_waitcnt lgkmcnt(0)
	v_cvt_pk_bf16_f32 v37, v16, v17
	ds_read2_b32 v[16:17], v29 offset0:24 offset1:57
	v_lshl_add_u64 v[40:41], v[42:43], 0, v[40:41]
	global_store_dwordx4 v[40:41], v[34:37], off
	v_or_b32_e32 v18, s10, v24
	v_mov_b32_e32 v41, v1
	s_waitcnt lgkmcnt(0)
	v_cvt_pk_bf16_f32 v34, v16, v17
	ds_read2_b32 v[16:17], v29 offset0:90 offset1:123
	s_waitcnt lgkmcnt(0)
	v_cvt_pk_bf16_f32 v35, v16, v17
	ds_read2_b32 v[16:17], v29 offset0:156 offset1:189
	s_waitcnt lgkmcnt(0)
	v_cvt_pk_bf16_f32 v36, v16, v17
	ds_read2_b32 v[16:17], v29 offset0:222 offset1:255
	v_lshlrev_b32_e32 v40, 11, v18
	s_waitcnt lgkmcnt(0)
	v_cvt_pk_bf16_f32 v37, v16, v17
	v_lshl_add_u64 v[16:17], v[42:43], 0, v[40:41]
	global_store_dwordx4 v[16:17], v[34:37], off
	s_waitcnt lgkmcnt(0)

.LBB0_2624:
	s_load_dwordx2 s[48:49], s[44:45], 0x130
	s_lshr_b32 s37, s37, 22
	s_mulk_i32 s37, 0x58
	s_sub_i32 s36, s36, s37
	s_lshl_b32 s37, s36, 7
	s_and_b32 s37, s37, 0x3ff80
	s_waitcnt lgkmcnt(0)
	s_add_u32 s48, s48, s37
	s_addc_u32 s49, s49, 0
	v_lshl_add_u64 v[16:17], s[48:49], 0, v[0:1]
	v_lshl_add_u64 v[16:17], v[16:17], 0, s[22:23]
	v_or_b32_e32 v250, s10, v21
	v_mad_u64_u32 v[248:249], s[48:49], v250, s34, v[16:17]
	global_load_dwordx4 v[212:215], v[248:249], off
	v_or_b32_e32 v250, s10, v22
	v_mad_u64_u32 v[248:249], s[48:49], v250, s34, v[16:17]
	global_load_dwordx4 v[216:219], v[248:249], off
	v_or_b32_e32 v250, s10, v24
	v_mad_u64_u32 v[248:249], s[48:49], v250, s34, v[16:17]
	global_load_dwordx4 v[220:223], v[248:249], off
	v_or_b32_e32 v250, s10, v25
	v_mad_u64_u32 v[248:249], s[48:49], v250, s34, v[16:17]
	global_load_dwordx4 v[224:227], v[248:249], off
	v_or_b32_e32 v250, s10, v26
	v_mad_u64_u32 v[248:249], s[48:49], v250, s34, v[16:17]
	global_load_dwordx4 v[228:231], v[248:249], off
	v_or_b32_e32 v250, s10, v27
	v_mad_u64_u32 v[248:249], s[48:49], v250, s34, v[16:17]
	global_load_dwordx4 v[232:235], v[248:249], off
	v_or_b32_e32 v250, s10, v28
	v_mad_u64_u32 v[248:249], s[48:49], v250, s34, v[16:17]
	global_load_dwordx4 v[236:239], v[248:249], off
	v_mad_u64_u32 v[34:35], s[48:49], v33, s34, v[16:17]
	global_load_dwordx4 v[34:37], v[34:35], off
	s_and_b64 vcc, exec, s[6:7]
	s_waitcnt vmcnt(0)
	v_pk_mul_f32 v[36:37], v[36:37], v[20:21] op_sel_hi:[1,0]
	v_pk_mul_f32 v[34:35], v[34:35], v[20:21] op_sel_hi:[1,0]
	v_or_b32_e32 v20, s10, v21
	ds_write2_b32 v31, v34, v35 offset1:1
	ds_write2_b32 v31, v36, v37 offset0:2 offset1:3
	s_cbranch_vccnz .LBB0_2626
	v_lshlrev_b32_e32 v18, 2, v20
	global_load_dword v18, v18, s[14:15]

.LBB0_2638:
	v_mad_u64_u32 v[16:17], s[6:7], v18, s34, v[16:17]
	s_lshl_b32 s6, s36, 5
	s_and_b32 s6, 0xffff, s6
	s_lshl_b32 s7, s6, 1
	v_add_u32_e32 v18, 0x14a0, v33
	s_and_b32 s6, s6, 0x60
	s_and_b32 s7, s7, 0x1f00
	v_add_u32_e32 v33, 0x14a8, v33
	s_or_b32 s6, s7, s6
	s_lshl_b32 s10, s10, 1
	v_mov_b32_e32 v41, v1
	v_lshl_add_u64 v[42:43], v[10:11], 0, s[10:11]
	s_waitcnt vmcnt(0)
	v_pk_mul_f32 v[34:35], v[236:237], v[20:21] op_sel_hi:[1,0]
	v_pk_mul_f32 v[16:17], v[238:239], v[20:21] op_sel_hi:[1,0]
	ds_write2_b32 v18, v34, v35 offset1:1
	ds_write2_b32 v33, v16, v17 offset1:1
	s_waitcnt lgkmcnt(0)
	v_or_b32_e32 v18, s6, v9
	v_lshlrev_b32_e32 v40, 11, v18
	ds_read2_b32 v[16:17], v29 offset1:33
	v_lshl_add_u64 v[40:41], v[42:43], 0, v[40:41]
	s_waitcnt lgkmcnt(0)
	v_cvt_pk_bf16_f32 v34, v16, v17
	ds_read2_b32 v[16:17], v29 offset0:66 offset1:99
	v_add_co_u32_e32 v40, vcc, s35, v40
	s_waitcnt lgkmcnt(0)
	v_cvt_pk_bf16_f32 v35, v16, v17
	ds_read2_b32 v[16:17], v29 offset0:132 offset1:165
	v_addc_co_u32_e32 v41, vcc, 0, v41, vcc
	v_or_b32_e32 v18, s6, v21
	s_waitcnt lgkmcnt(0)
	v_cvt_pk_bf16_f32 v36, v16, v17
	ds_read2_b32 v[16:17], v29 offset0:198 offset1:231
	s_waitcnt lgkmcnt(0)
	v_cvt_pk_bf16_f32 v37, v16, v17
	global_store_dwordx4 v[40:41], v[34:37], off
	v_mov_b32_e32 v41, v1
	v_lshlrev_b32_e32 v40, 11, v18
	ds_read2_b32 v[16:17], v29 offset0:8 offset1:41
	v_lshl_add_u64 v[40:41], v[42:43], 0, v[40:41]
	s_waitcnt lgkmcnt(0)
	v_cvt_pk_bf16_f32 v34, v16, v17
	ds_read2_b32 v[16:17], v29 offset0:74 offset1:107
	v_add_co_u32_e32 v40, vcc, s35, v40
	s_waitcnt lgkmcnt(0)
	v_cvt_pk_bf16_f32 v35, v16, v17
	ds_read2_b32 v[16:17], v29 offset0:140 offset1:173
	v_addc_co_u32_e32 v41, vcc, 0, v41, vcc
	v_or_b32_e32 v18, s6, v22
	s_waitcnt lgkmcnt(0)
	v_cvt_pk_bf16_f32 v36, v16, v17
	ds_read2_b32 v[16:17], v29 offset0:206 offset1:239
	s_waitcnt lgkmcnt(0)
	v_cvt_pk_bf16_f32 v37, v16, v17
	global_store_dwordx4 v[40:41], v[34:37], off
	v_mov_b32_e32 v41, v1
	v_lshlrev_b32_e32 v40, 11, v18
	ds_read2_b32 v[16:17], v29 offset0:16 offset1:49
	v_lshl_add_u64 v[40:41], v[42:43], 0, v[40:41]
	s_waitcnt lgkmcnt(0)
	v_cvt_pk_bf16_f32 v34, v16, v17
	ds_read2_b32 v[16:17], v29 offset0:82 offset1:115
	v_add_co_u32_e32 v40, vcc, s35, v40
	s_waitcnt lgkmcnt(0)
	v_cvt_pk_bf16_f32 v35, v16, v17
	ds_read2_b32 v[16:17], v29 offset0:148 offset1:181
	v_addc_co_u32_e32 v41, vcc, 0, v41, vcc
	v_or_b32_e32 v18, s6, v24
	s_waitcnt lgkmcnt(0)
	v_cvt_pk_bf16_f32 v36, v16, v17
	ds_read2_b32 v[16:17], v29 offset0:214 offset1:247
	s_waitcnt lgkmcnt(0)
	v_cvt_pk_bf16_f32 v37, v16, v17
	global_store_dwordx4 v[40:41], v[34:37], off
	v_mov_b32_e32 v41, v1
	v_lshlrev_b32_e32 v40, 11, v18
	ds_read2_b32 v[16:17], v29 offset0:24 offset1:57
	v_lshl_add_u64 v[40:41], v[42:43], 0, v[40:41]
	s_waitcnt lgkmcnt(0)
	v_cvt_pk_bf16_f32 v34, v16, v17
	ds_read2_b32 v[16:17], v29 offset0:90 offset1:123
	v_add_co_u32_e32 v40, vcc, 0x40000, v40
	s_waitcnt lgkmcnt(0)
	v_cvt_pk_bf16_f32 v35, v16, v17
	ds_read2_b32 v[16:17], v29 offset0:156 offset1:189
	v_addc_co_u32_e32 v41, vcc, 0, v41, vcc
	s_waitcnt lgkmcnt(0)
	v_cvt_pk_bf16_f32 v36, v16, v17
	ds_read2_b32 v[16:17], v29 offset0:222 offset1:255
	s_waitcnt lgkmcnt(0)
	v_cvt_pk_bf16_f32 v37, v16, v17
	global_store_dwordx4 v[40:41], v[34:37], off
	s_waitcnt lgkmcnt(0)
